# residual and QKV epilogues: cross-lane xor16/xor32 sums via v_permlane16/32_swap (VALU) instead of ds_bpermute + lgkmcnt round trips
# speedup vs baseline: 1.0002x; 1.0002x over previous
; #define PG8_STAGE(bufoff, gbase, voff) do { _Pragma("unroll") for (int _i = 0; _i < 2; ++_i) \
;         __builtin_amdgcn_global_load_lds((const unsigned*)((const char*)(gbase) + (voff)[_i]), (LAS unsigned*)(lds + (bufoff) + ldsw + _i * 8192), 16, 0, 0); } while (0)
; #define PG8_LDA(dst, b, h) do { _Pragma("unroll") for (int m = 0; m < 4; ++m) _Pragma("unroll") for (int k = 0; k < 2; ++k) dst[m][k] = *(const LAS bf16x8*)(lds + PG8_SA(b, h) + aoff + m * 2048 + k * 1024); } while (0)
; #define PG8_LDB(dst, b, h) do { _Pragma("unroll") for (int n = 0; n < 2; ++n) _Pragma("unroll") for (int k = 0; k < 2; ++k) dst[n][k] = *(const LAS bf16x8*)(lds + PG8_SB(b, h) + boff + n * 2048 + k * 1024); } while (0)
; #define PG8_MMA(ai, bj, At, Bt) do { __builtin_amdgcn_s_setprio(1); _Pragma("unroll") for (int m = 0; m < 4; ++m) _Pragma("unroll") for (int n = 0; n < 2; ++n) _Pragma("unroll") for (int k = 0; k < 2; ++k) \
;         acc[ai][bj][m][n] = __builtin_amdgcn_mfma_f32_16x16x32_bf16(Bt[n][k], At[m][k], acc[ai][bj][m][n], 0, 0, 0); __builtin_amdgcn_s_setprio(0); } while (0)
; #define PG8_WAIT_V(n) asm volatile("s_waitcnt vmcnt(" #n ")" ::: "memory")
; #define PG8_WAIT_L(n) asm volatile("s_waitcnt lgkmcnt(" #n ")" ::: "memory")
; #define PG8_BAR __builtin_amdgcn_s_barrier()
; #define PG8_SCHED __builtin_amdgcn_sched_barrier(0)
; template <class Epi, bool ALIGN_EPI>
; __device__ __forceinline__ void gemm_phase(LAS unsigned char* lds, const Gemm g, int G, int cid, const Epi& E) {
;     ...
;         for (int t = 0; t < nt; t += 2) {
;             const bool last = (t == nt - 2);
;             const char* a1 = cA + (size_t)(t + 1) * kA;
;             const char* a2 = last ? nA : cA + (size_t)(t + 2) * kA; const char* b2 = last ? nB : cB + (size_t)(t + 2) * kB;
;             const char* a3 = a2 + kA; const char* b3 = b2 + kB;
;             PG8_LDB(B0, 0, 0); PG8_LDB(B1, 0, 1); PG8_SCHED; PG8_LDA(At, 0, 0); PG8_STAGE(PG8_SA(1, 1), a1 + hA, voffA);
;             PG8_WAIT_V(8); PG8_WAIT_L(0); PG8_BAR; PG8_MMA(0, 0, At, B0); PG8_MMA(0, 1, At, B1); PG8_BAR; PG8_SCHED;
;             PG8_LDA(At, 0, 1); PG8_STAGE(PG8_SB(0, 0), b2, voffB); PG8_STAGE(PG8_SB(0, 1), b2 + hB, voffB); PG8_STAGE(PG8_SA(0, 0), a2, voffA);
;             PG8_WAIT_V(8); PG8_WAIT_L(0); PG8_BAR; PG8_MMA(1, 0, At, B0); PG8_MMA(1, 1, At, B1); PG8_BAR; PG8_SCHED;
.LBB0_169:
	s_add_u32 s44, s50, 0x100
	s_addc_u32 s45, s51, 0
	s_add_i32 s6, 0, 0x10000
	s_cmp_eq_u32 s79, 4
	s_cselect_b32 s55, s43, s45
	s_cselect_b32 s54, s42, s44
	s_cselect_b32 s53, s30, s78
	s_cselect_b32 s52, s76, s77
	s_add_i32 s86, 0, 0x14000
	v_add_u32_e32 v84, s6, v212
	v_add_u32_e32 v100, s86, v212
	ds_read_b128 v[68:71], v84
	ds_read_b128 v[76:79], v84 offset:1024
	ds_read_b128 v[80:83], v84 offset:2048
	ds_read_b128 v[84:87], v84 offset:3072
	ds_read_b128 v[88:91], v100
	ds_read_b128 v[92:95], v100 offset:1024
	ds_read_b128 v[96:99], v100 offset:2048
	ds_read_b128 v[100:103], v100 offset:3072
	v_lshl_add_u64 v[198:199], s[50:51], 0, v[184:185]
	s_add_i32 m0, s24, 0xc000
	ds_read_b128 v[164:167], v214
	ds_read_b128 v[168:171], v214 offset:1024
	ds_read_b128 v[172:175], v214 offset:2048
	ds_read_b128 v[176:179], v214 offset:3072
	ds_read_b128 v[188:191], v214 offset:4096
	ds_read_b128 v[206:209], v214 offset:5120
	ds_read_b128 v[216:219], v214 offset:6144
	ds_read_b128 v[220:223], v214 offset:7168
	global_load_lds_dwordx4 v[198:199], off
	v_lshl_add_u64 v[198:199], s[50:51], 0, v[186:187]
	s_add_i32 m0, s24, 0xe000
	s_nop 0
	global_load_lds_dwordx4 v[198:199], off
	s_waitcnt vmcnt(8)
	s_waitcnt lgkmcnt(0)
	s_barrier
	s_setprio 1
	s_waitcnt lgkmcnt(0)
	v_mfma_f32_16x16x32_bf16 v[160:163], v[68:71], v[164:167], v[160:163]
	v_mfma_f32_16x16x32_bf16 v[156:159], v[80:83], v[164:167], v[156:159]
	v_mfma_f32_16x16x32_bf16 v[144:147], v[68:71], v[172:175], v[144:147]
	v_mfma_f32_16x16x32_bf16 v[140:143], v[80:83], v[172:175], v[140:143]
	v_mfma_f32_16x16x32_bf16 v[124:127], v[68:71], v[188:191], v[124:127]
	v_mfma_f32_16x16x32_bf16 v[120:123], v[80:83], v[188:191], v[120:123]
	v_mfma_f32_16x16x32_bf16 v[108:111], v[68:71], v[216:219], v[108:111]
	v_mfma_f32_16x16x32_bf16 v[104:107], v[80:83], v[216:219], v[104:107]
	v_mfma_f32_16x16x32_bf16 v[160:163], v[76:79], v[168:171], v[160:163]
	v_mfma_f32_16x16x32_bf16 v[156:159], v[84:87], v[168:171], v[156:159]
	v_mfma_f32_16x16x32_bf16 v[144:147], v[76:79], v[176:179], v[144:147]
	v_mfma_f32_16x16x32_bf16 v[140:143], v[84:87], v[176:179], v[140:143]
	v_mfma_f32_16x16x32_bf16 v[124:127], v[76:79], v[206:209], v[124:127]
	v_mfma_f32_16x16x32_bf16 v[120:123], v[84:87], v[206:209], v[120:123]
	v_mfma_f32_16x16x32_bf16 v[108:111], v[76:79], v[220:223], v[108:111]
	v_mfma_f32_16x16x32_bf16 v[104:107], v[84:87], v[220:223], v[104:107]
	s_setprio 0
	s_setprio 1
	v_mfma_f32_16x16x32_bf16 v[152:155], v[88:91], v[164:167], v[152:155]
	v_mfma_f32_16x16x32_bf16 v[148:151], v[96:99], v[164:167], v[148:151]
	v_mfma_f32_16x16x32_bf16 v[132:135], v[88:91], v[172:175], v[132:135]
	v_mfma_f32_16x16x32_bf16 v[128:131], v[96:99], v[172:175], v[128:131]
	v_mfma_f32_16x16x32_bf16 v[116:119], v[88:91], v[188:191], v[116:119]
	v_mfma_f32_16x16x32_bf16 v[112:115], v[96:99], v[188:191], v[112:115]
	v_mfma_f32_16x16x32_bf16 v[72:75], v[88:91], v[216:219], v[72:75]
	v_mfma_f32_16x16x32_bf16 v[64:67], v[96:99], v[216:219], v[64:67]
	v_mfma_f32_16x16x32_bf16 v[152:155], v[92:95], v[168:171], v[152:155]
	v_mfma_f32_16x16x32_bf16 v[148:151], v[100:103], v[168:171], v[148:151]
	v_mfma_f32_16x16x32_bf16 v[132:135], v[92:95], v[176:179], v[132:135]
	v_mfma_f32_16x16x32_bf16 v[128:131], v[100:103], v[176:179], v[128:131]
	v_mfma_f32_16x16x32_bf16 v[116:119], v[92:95], v[206:209], v[116:119]
	v_mfma_f32_16x16x32_bf16 v[112:115], v[100:103], v[206:209], v[112:115]
	v_mfma_f32_16x16x32_bf16 v[72:75], v[92:95], v[220:223], v[72:75]
	v_mfma_f32_16x16x32_bf16 v[64:67], v[100:103], v[220:223], v[64:67]
	s_setprio 0
	s_barrier
	s_add_i32 s6, s6, s23
	v_lshl_add_u64 v[198:199], s[52:53], 0, v[138:139]
	s_mov_b32 m0, s6
	ds_read_b128 v[164:167], v214 offset:16384
	ds_read_b128 v[168:171], v214 offset:17408
	ds_read_b128 v[172:175], v214 offset:18432
	ds_read_b128 v[176:179], v214 offset:19456
	ds_read_b128 v[188:191], v214 offset:20480
	ds_read_b128 v[206:209], v214 offset:21504
	ds_read_b128 v[216:219], v214 offset:22528
	ds_read_b128 v[220:223], v214 offset:23552
	global_load_lds_dwordx4 v[198:199], off
	s_add_i32 m0, s6, 0x2000
	s_add_u32 s6, s52, 0x2000
	v_lshl_add_u64 v[198:199], s[52:53], 0, v[136:137]
	s_addc_u32 s7, s53, 0
	s_add_i32 s50, s86, s23
	global_load_lds_dwordx4 v[198:199], off
	v_lshl_add_u64 v[198:199], s[6:7], 0, v[138:139]
	s_mov_b32 m0, s50
	v_lshl_add_u64 v[200:201], s[54:55], 0, v[180:181]
	global_load_lds_dwordx4 v[198:199], off
	v_lshl_add_u64 v[198:199], s[6:7], 0, v[136:137]
	s_add_i32 m0, s50, 0x2000
	s_nop 0
	global_load_lds_dwordx4 v[198:199], off
	v_lshl_add_u64 v[198:199], s[54:55], 0, v[182:183]
	s_mov_b32 m0, s24
	s_nop 0
	global_load_lds_dwordx4 v[198:199], off
	s_mov_b32 m0, s25
	s_nop 0
	global_load_lds_dwordx4 v[200:201], off
	s_waitcnt vmcnt(8)
	s_waitcnt lgkmcnt(0)
	s_barrier
; #define PG8_STAGE(bufoff, gbase, voff) do { _Pragma("unroll") for (int _i = 0; _i < 2; ++_i) \
;         __builtin_amdgcn_global_load_lds((const unsigned*)((const char*)(gbase) + (voff)[_i]), (LAS unsigned*)(lds + (bufoff) + ldsw + _i * 8192), 16, 0, 0); } while (0)
; #define PG8_LDA(dst, b, h) do { _Pragma("unroll") for (int m = 0; m < 4; ++m) _Pragma("unroll") for (int k = 0; k < 2; ++k) dst[m][k] = *(const LAS bf16x8*)(lds + PG8_SA(b, h) + aoff + m * 2048 + k * 1024); } while (0)
; #define PG8_LDB(dst, b, h) do { _Pragma("unroll") for (int n = 0; n < 2; ++n) _Pragma("unroll") for (int k = 0; k < 2; ++k) dst[n][k] = *(const LAS bf16x8*)(lds + PG8_SB(b, h) + boff + n * 2048 + k * 1024); } while (0)
; #define PG8_MMA(ai, bj, At, Bt) do { __builtin_amdgcn_s_setprio(1); _Pragma("unroll") for (int m = 0; m < 4; ++m) _Pragma("unroll") for (int n = 0; n < 2; ++n) _Pragma("unroll") for (int k = 0; k < 2; ++k) \
;         acc[ai][bj][m][n] = __builtin_amdgcn_mfma_f32_16x16x32_bf16(Bt[n][k], At[m][k], acc[ai][bj][m][n], 0, 0, 0); __builtin_amdgcn_s_setprio(0); } while (0)
; #define PG8_WAIT_V(n) asm volatile("s_waitcnt vmcnt(" #n ")" ::: "memory")
; #define PG8_WAIT_L(n) asm volatile("s_waitcnt lgkmcnt(" #n ")" ::: "memory")
; #define PG8_BAR __builtin_amdgcn_s_barrier()
; #define PG8_SCHED __builtin_amdgcn_sched_barrier(0)
; template <class Epi, bool ALIGN_EPI>
; __device__ __forceinline__ void gemm_phase(LAS unsigned char* lds, const Gemm g, int G, int cid, const Epi& E) {
;     ...
;             PG8_WAIT_V(8); PG8_WAIT_L(0); PG8_BAR; PG8_MMA(1, 0, At, B0); PG8_MMA(1, 1, At, B1); PG8_BAR; PG8_SCHED;
;             PG8_LDB(B0, 1, 0); PG8_LDB(B1, 1, 1); PG8_SCHED; PG8_LDA(At, 1, 0); PG8_STAGE(PG8_SA(0, 1), a2 + hA, voffA);
;             PG8_WAIT_V(8); PG8_WAIT_L(0); PG8_BAR; PG8_MMA(0, 0, At, B0); PG8_MMA(0, 1, At, B1); PG8_BAR; PG8_SCHED;
	s_setprio 1
	s_waitcnt lgkmcnt(0)
	v_mfma_f32_16x16x32_bf16 v[60:63], v[68:71], v[164:167], v[60:63]
	v_mfma_f32_16x16x32_bf16 v[56:59], v[80:83], v[164:167], v[56:59]
	v_mfma_f32_16x16x32_bf16 v[44:47], v[68:71], v[172:175], v[44:47]
	v_mfma_f32_16x16x32_bf16 v[40:43], v[80:83], v[172:175], v[40:43]
	v_mfma_f32_16x16x32_bf16 v[28:31], v[68:71], v[188:191], v[28:31]
	v_mfma_f32_16x16x32_bf16 v[24:27], v[80:83], v[188:191], v[24:27]
	v_mfma_f32_16x16x32_bf16 v[12:15], v[68:71], v[216:219], v[12:15]
	v_mfma_f32_16x16x32_bf16 v[8:11], v[80:83], v[216:219], v[8:11]
	v_mfma_f32_16x16x32_bf16 v[60:63], v[76:79], v[168:171], v[60:63]
	v_mfma_f32_16x16x32_bf16 v[56:59], v[84:87], v[168:171], v[56:59]
	v_mfma_f32_16x16x32_bf16 v[44:47], v[76:79], v[176:179], v[44:47]
	v_mfma_f32_16x16x32_bf16 v[40:43], v[84:87], v[176:179], v[40:43]
	v_mfma_f32_16x16x32_bf16 v[28:31], v[76:79], v[206:209], v[28:31]
	v_mfma_f32_16x16x32_bf16 v[24:27], v[84:87], v[206:209], v[24:27]
	v_mfma_f32_16x16x32_bf16 v[12:15], v[76:79], v[220:223], v[12:15]
	v_mfma_f32_16x16x32_bf16 v[8:11], v[84:87], v[220:223], v[8:11]
	s_setprio 0
	s_setprio 1
	v_mfma_f32_16x16x32_bf16 v[52:55], v[88:91], v[164:167], v[52:55]
	v_mfma_f32_16x16x32_bf16 v[48:51], v[96:99], v[164:167], v[48:51]
	v_mfma_f32_16x16x32_bf16 v[36:39], v[88:91], v[172:175], v[36:39]
	v_mfma_f32_16x16x32_bf16 v[32:35], v[96:99], v[172:175], v[32:35]
	v_mfma_f32_16x16x32_bf16 v[20:23], v[88:91], v[188:191], v[20:23]
	v_mfma_f32_16x16x32_bf16 v[16:19], v[96:99], v[188:191], v[16:19]
	v_mfma_f32_16x16x32_bf16 v[4:7], v[88:91], v[216:219], v[4:7]
	v_mfma_f32_16x16x32_bf16 v[0:3], v[96:99], v[216:219], v[0:3]
	v_mfma_f32_16x16x32_bf16 v[52:55], v[92:95], v[168:171], v[52:55]
	v_mfma_f32_16x16x32_bf16 v[48:51], v[100:103], v[168:171], v[48:51]
	v_mfma_f32_16x16x32_bf16 v[36:39], v[92:95], v[176:179], v[36:39]
	v_mfma_f32_16x16x32_bf16 v[32:35], v[100:103], v[176:179], v[32:35]
	v_mfma_f32_16x16x32_bf16 v[20:23], v[92:95], v[206:209], v[20:23]
	v_mfma_f32_16x16x32_bf16 v[16:19], v[100:103], v[206:209], v[16:19]
	v_mfma_f32_16x16x32_bf16 v[4:7], v[92:95], v[220:223], v[4:7]
	v_mfma_f32_16x16x32_bf16 v[0:3], v[100:103], v[220:223], v[0:3]
	s_setprio 0
	s_barrier
	s_add_i32 s50, 0, 0x18000
	s_add_i32 s51, 0, 0x1c000
	v_add_u32_e32 v84, s50, v212
	v_add_u32_e32 v100, s51, v212
	ds_read_b128 v[68:71], v84
	ds_read_b128 v[76:79], v84 offset:1024
	ds_read_b128 v[80:83], v84 offset:2048
	ds_read_b128 v[84:87], v84 offset:3072
	ds_read_b128 v[88:91], v100
	ds_read_b128 v[92:95], v100 offset:1024
	ds_read_b128 v[96:99], v100 offset:2048
	ds_read_b128 v[100:103], v100 offset:3072
	s_add_u32 s6, s54, 0x84000
	s_addc_u32 s7, s55, 0
	s_mov_b32 m0, s56
	v_lshl_add_u64 v[210:211], s[6:7], 0, v[182:183]
	ds_read_b128 v[164:167], v214 offset:32768
	ds_read_b128 v[168:171], v214 offset:33792
	ds_read_b128 v[172:175], v214 offset:34816
	ds_read_b128 v[176:179], v214 offset:35840
	ds_read_b128 v[188:191], v214 offset:36864
	ds_read_b128 v[206:209], v214 offset:37888
	ds_read_b128 v[216:219], v214 offset:38912
	ds_read_b128 v[220:223], v214 offset:39936
	global_load_lds_dwordx4 v[210:211], off
	v_lshl_add_u64 v[210:211], s[6:7], 0, v[180:181]
	s_mov_b32 m0, s57
	s_nop 0
	global_load_lds_dwordx4 v[210:211], off
	s_waitcnt vmcnt(8)
	s_waitcnt lgkmcnt(0)
	s_barrier
	s_setprio 1
	s_waitcnt lgkmcnt(0)
	v_mfma_f32_16x16x32_bf16 v[160:163], v[68:71], v[164:167], v[160:163]
	v_mfma_f32_16x16x32_bf16 v[156:159], v[80:83], v[164:167], v[156:159]
	v_mfma_f32_16x16x32_bf16 v[144:147], v[68:71], v[172:175], v[144:147]
	v_mfma_f32_16x16x32_bf16 v[140:143], v[80:83], v[172:175], v[140:143]
	v_mfma_f32_16x16x32_bf16 v[124:127], v[68:71], v[188:191], v[124:127]
	v_mfma_f32_16x16x32_bf16 v[120:123], v[80:83], v[188:191], v[120:123]
	v_mfma_f32_16x16x32_bf16 v[108:111], v[68:71], v[216:219], v[108:111]
	v_mfma_f32_16x16x32_bf16 v[104:107], v[80:83], v[216:219], v[104:107]
	v_mfma_f32_16x16x32_bf16 v[160:163], v[76:79], v[168:171], v[160:163]
	v_mfma_f32_16x16x32_bf16 v[156:159], v[84:87], v[168:171], v[156:159]
	v_mfma_f32_16x16x32_bf16 v[144:147], v[76:79], v[176:179], v[144:147]
	v_mfma_f32_16x16x32_bf16 v[140:143], v[84:87], v[176:179], v[140:143]
	v_mfma_f32_16x16x32_bf16 v[124:127], v[76:79], v[206:209], v[124:127]
	v_mfma_f32_16x16x32_bf16 v[120:123], v[84:87], v[206:209], v[120:123]
	v_mfma_f32_16x16x32_bf16 v[108:111], v[76:79], v[220:223], v[108:111]
	v_mfma_f32_16x16x32_bf16 v[104:107], v[84:87], v[220:223], v[104:107]
	s_setprio 0
	s_setprio 1
	v_mfma_f32_16x16x32_bf16 v[152:155], v[88:91], v[164:167], v[152:155]
	v_mfma_f32_16x16x32_bf16 v[148:151], v[96:99], v[164:167], v[148:151]
	v_mfma_f32_16x16x32_bf16 v[132:135], v[88:91], v[172:175], v[132:135]
	v_mfma_f32_16x16x32_bf16 v[128:131], v[96:99], v[172:175], v[128:131]
	v_mfma_f32_16x16x32_bf16 v[116:119], v[88:91], v[188:191], v[116:119]
	v_mfma_f32_16x16x32_bf16 v[112:115], v[96:99], v[188:191], v[112:115]
	v_mfma_f32_16x16x32_bf16 v[72:75], v[88:91], v[216:219], v[72:75]
	v_mfma_f32_16x16x32_bf16 v[64:67], v[96:99], v[216:219], v[64:67]
	v_mfma_f32_16x16x32_bf16 v[152:155], v[92:95], v[168:171], v[152:155]
	v_mfma_f32_16x16x32_bf16 v[148:151], v[100:103], v[168:171], v[148:151]
	v_mfma_f32_16x16x32_bf16 v[132:135], v[92:95], v[176:179], v[132:135]
	v_mfma_f32_16x16x32_bf16 v[128:131], v[100:103], v[176:179], v[128:131]
	v_mfma_f32_16x16x32_bf16 v[116:119], v[92:95], v[206:209], v[116:119]
	v_mfma_f32_16x16x32_bf16 v[112:115], v[100:103], v[206:209], v[112:115]
	v_mfma_f32_16x16x32_bf16 v[72:75], v[92:95], v[220:223], v[72:75]
	v_mfma_f32_16x16x32_bf16 v[64:67], v[100:103], v[220:223], v[64:67]
	s_setprio 0
	s_barrier
; #define PG8_STAGE(bufoff, gbase, voff) do { _Pragma("unroll") for (int _i = 0; _i < 2; ++_i) \
;         __builtin_amdgcn_global_load_lds((const unsigned*)((const char*)(gbase) + (voff)[_i]), (LAS unsigned*)(lds + (bufoff) + ldsw + _i * 8192), 16, 0, 0); } while (0)
; #define PG8_LDA(dst, b, h) do { _Pragma("unroll") for (int m = 0; m < 4; ++m) _Pragma("unroll") for (int k = 0; k < 2; ++k) dst[m][k] = *(const LAS bf16x8*)(lds + PG8_SA(b, h) + aoff + m * 2048 + k * 1024); } while (0)
; #define PG8_WAIT_V(n) asm volatile("s_waitcnt vmcnt(" #n ")" ::: "memory")
; #define PG8_WAIT_L(n) asm volatile("s_waitcnt lgkmcnt(" #n ")" ::: "memory")
; template <class Epi, bool ALIGN_EPI>
; __device__ __forceinline__ void gemm_phase(LAS unsigned char* lds, const Gemm g, int G, int cid, const Epi& E) {
;     ...
;             PG8_WAIT_V(8); PG8_WAIT_L(0); PG8_BAR; PG8_MMA(0, 0, At, B0); PG8_MMA(0, 1, At, B1); PG8_BAR; PG8_SCHED;
;             PG8_LDA(At, 1, 1); PG8_STAGE(PG8_SB(1, 0), b3, voffB); PG8_STAGE(PG8_SB(1, 1), b3 + hB, voffB); PG8_STAGE(PG8_SA(1, 0), a3, voffA);
;             PG8_WAIT_V(8); PG8_WAIT_L(0); PG8_BAR; PG8_MMA(1, 0, At, B0); PG8_MMA(1, 1, At, B1); PG8_BAR; PG8_SCHED;
;         }
;     __device__ __forceinline__ void operator()(const f32x4 (&acc)[2][2][4][2], const Unit& u, int wr, int wc, int fr, int fq, const LAS float*) const {
;         const int row0 = u.pm * BM + wr * 64 + fr, col0 = u.pn * BM + wc * 32 + 8 * fq;
;         f32x4 bv[2][2], sv[2][2];
; #pragma unroll
;         for (int bj = 0; bj < 2; ++bj)
; #pragma unroll
;             for (int n = 0; n < 2; ++n) { bv[bj][n] = HB ? *(const f32x4*)(bias + col0 + bj * HALF + 4 * n) : (f32x4){0.f, 0.f, 0.f, 0.f};
;                                            sv[bj][n] = HB ? *(const f32x4*)(scale + col0 + bj * HALF + 4 * n) : (f32x4){1.f, 1.f, 1.f, 1.f}; }
;         constexpr int NB = HB ? 4 : 2, MB = 4 / (NB / 2);
; #pragma unroll
;         for (int am = 0; am < NB; ++am) { const int ai = am / (NB / 2), m0 = (am % (NB / 2)) * MB;
;             f32x4 xo[4][2][2];
; #pragma unroll
;             for (int m = m0; m < m0 + MB; ++m) { const float* xr = Xs + (size_t)(row0 + ai * HALF + m * 16) * DM + col0;
; #pragma unroll
;                 for (int bj = 0; bj < 2; ++bj) { xo[m][bj][0] = *(const f32x4*)(xr + bj * HALF); xo[m][bj][1] = *(const f32x4*)(xr + bj * HALF + 4); } }
	s_add_u32 s6, s52, 0x10000
	s_addc_u32 s7, s53, 0
	s_add_i32 s50, s50, s23
	v_lshl_add_u64 v[210:211], s[6:7], 0, v[138:139]
	s_mov_b32 m0, s50
	ds_read_b128 v[164:167], v214 offset:49152
	ds_read_b128 v[168:171], v214 offset:50176
	ds_read_b128 v[172:175], v214 offset:51200
	ds_read_b128 v[176:179], v214 offset:52224
	ds_read_b128 v[188:191], v214 offset:53248
	ds_read_b128 v[206:209], v214 offset:54272
	ds_read_b128 v[216:219], v214 offset:55296
	ds_read_b128 v[220:223], v214 offset:56320
	global_load_lds_dwordx4 v[210:211], off
	s_add_i32 m0, s50, 0x2000
	v_lshl_add_u64 v[210:211], s[6:7], 0, v[136:137]
	s_add_u32 s6, s52, 0x12000
	s_addc_u32 s7, s53, 0
	s_add_i32 s50, s51, s23
	global_load_lds_dwordx4 v[210:211], off
	v_lshl_add_u64 v[210:211], s[6:7], 0, v[138:139]
	s_mov_b32 m0, s50
	v_lshl_add_u64 v[198:199], v[198:199], 0, s[36:37]
	global_load_lds_dwordx4 v[210:211], off
	v_lshl_add_u64 v[210:211], s[6:7], 0, v[136:137]
	s_add_i32 m0, s50, 0x2000
	s_nop 0
	global_load_lds_dwordx4 v[210:211], off
	s_mov_b32 m0, s59
	s_nop 0
	global_load_lds_dwordx4 v[198:199], off
	v_lshl_add_u64 v[198:199], v[200:201], 0, s[36:37]
	s_mov_b32 m0, s72
	s_nop 0
	global_load_lds_dwordx4 v[198:199], off
	s_waitcnt vmcnt(8)
	s_waitcnt lgkmcnt(0)
	s_barrier
	s_setprio 1
	s_waitcnt lgkmcnt(0)
	v_mfma_f32_16x16x32_bf16 v[60:63], v[68:71], v[164:167], v[60:63]
	v_mfma_f32_16x16x32_bf16 v[56:59], v[80:83], v[164:167], v[56:59]
	v_mfma_f32_16x16x32_bf16 v[44:47], v[68:71], v[172:175], v[44:47]
	v_mfma_f32_16x16x32_bf16 v[40:43], v[80:83], v[172:175], v[40:43]
	v_mfma_f32_16x16x32_bf16 v[28:31], v[68:71], v[188:191], v[28:31]
	v_mfma_f32_16x16x32_bf16 v[24:27], v[80:83], v[188:191], v[24:27]
	v_mfma_f32_16x16x32_bf16 v[12:15], v[68:71], v[216:219], v[12:15]
	v_mfma_f32_16x16x32_bf16 v[8:11], v[80:83], v[216:219], v[8:11]
	v_mfma_f32_16x16x32_bf16 v[60:63], v[76:79], v[168:171], v[60:63]
	v_mfma_f32_16x16x32_bf16 v[56:59], v[84:87], v[168:171], v[56:59]
	v_mfma_f32_16x16x32_bf16 v[44:47], v[76:79], v[176:179], v[44:47]
	v_mfma_f32_16x16x32_bf16 v[40:43], v[84:87], v[176:179], v[40:43]
	v_mfma_f32_16x16x32_bf16 v[28:31], v[76:79], v[206:209], v[28:31]
	v_mfma_f32_16x16x32_bf16 v[24:27], v[84:87], v[206:209], v[24:27]
	v_mfma_f32_16x16x32_bf16 v[12:15], v[76:79], v[220:223], v[12:15]
	v_mfma_f32_16x16x32_bf16 v[8:11], v[84:87], v[220:223], v[8:11]
	s_setprio 0
	s_setprio 1
	v_mfma_f32_16x16x32_bf16 v[52:55], v[88:91], v[164:167], v[52:55]
	v_mfma_f32_16x16x32_bf16 v[48:51], v[96:99], v[164:167], v[48:51]
	v_mfma_f32_16x16x32_bf16 v[36:39], v[88:91], v[172:175], v[36:39]
	v_mfma_f32_16x16x32_bf16 v[32:35], v[96:99], v[172:175], v[32:35]
	v_mfma_f32_16x16x32_bf16 v[20:23], v[88:91], v[188:191], v[20:23]
	v_mfma_f32_16x16x32_bf16 v[16:19], v[96:99], v[188:191], v[16:19]
	v_mfma_f32_16x16x32_bf16 v[4:7], v[88:91], v[216:219], v[4:7]
	v_mfma_f32_16x16x32_bf16 v[0:3], v[96:99], v[216:219], v[0:3]
	v_mfma_f32_16x16x32_bf16 v[52:55], v[92:95], v[168:171], v[52:55]
	v_mfma_f32_16x16x32_bf16 v[48:51], v[100:103], v[168:171], v[48:51]
	v_mfma_f32_16x16x32_bf16 v[36:39], v[92:95], v[176:179], v[36:39]
	v_mfma_f32_16x16x32_bf16 v[32:35], v[100:103], v[176:179], v[32:35]
	v_mfma_f32_16x16x32_bf16 v[20:23], v[92:95], v[206:209], v[20:23]
	v_mfma_f32_16x16x32_bf16 v[16:19], v[100:103], v[206:209], v[16:19]
	v_mfma_f32_16x16x32_bf16 v[4:7], v[92:95], v[220:223], v[4:7]
	v_mfma_f32_16x16x32_bf16 v[0:3], v[100:103], v[220:223], v[0:3]
	s_setprio 0
	s_barrier
	s_add_i32 s79, s79, 2
	s_add_u32 s77, s77, 0x20000
	s_addc_u32 s78, s78, 0
	s_cmp_lt_u32 s79, 6
	s_mov_b64 s[50:51], s[44:45]
	s_cbranch_scc1 .LBB0_169
	v_lshl_or_b32 v188, s12, 8, v213
	v_ashrrev_i32_e32 v189, 31, v188
	v_lshl_add_u32 v190, s13, 8, v197
	v_lshlrev_b64 v[198:199], 2, v[188:189]
	v_ashrrev_i32_e32 v191, 31, v190
	v_lshl_add_u64 v[206:207], s[82:83], 0, v[198:199]
	v_lshlrev_b64 v[200:201], 13, v[190:191]
	v_lshl_add_u64 v[68:69], s[28:29], 0, v[198:199]
	v_lshl_add_u64 v[80:81], s[46:47], 0, v[198:199]
	v_lshl_add_u64 v[164:165], v[206:207], 0, v[200:201]
	global_load_dwordx4 v[92:95], v[68:69], off offset:16
	global_load_dwordx4 v[100:103], v[68:69], off
	global_load_dwordx4 v[88:91], v[80:81], off offset:16
	global_load_dwordx4 v[96:99], v[80:81], off
	global_load_dwordx4 v[76:79], v[68:69], off offset:528
	global_load_dwordx4 v[84:87], v[68:69], off offset:512
	s_nop 0
	global_load_dwordx4 v[68:71], v[80:81], off offset:528
	s_nop 0
	global_load_dwordx4 v[80:83], v[80:81], off offset:512
	s_nop 0
	global_load_dwordx4 v[216:219], v[164:165], off offset:16
	global_load_dwordx4 v[220:223], v[164:165], off
	global_load_dwordx4 v[224:227], v[164:165], off offset:528
	global_load_dwordx4 v[228:231], v[164:165], off offset:512
	v_or_b32_e32 v208, 16, v190
	v_ashrrev_i32_e32 v209, 31, v208
	v_lshlrev_b64 v[210:211], 13, v[208:209]
	v_lshl_add_u64 v[168:169], v[206:207], 0, v[210:211]
	global_load_dwordx4 v[172:175], v[168:169], off offset:16
	global_load_dwordx4 v[176:179], v[168:169], off
	global_load_dwordx4 v[164:167], v[168:169], off offset:528
	s_nop 0
	global_load_dwordx4 v[168:171], v[168:169], off offset:512
	v_lshl_add_u64 v[200:201], s[82:83], 0, v[200:201]
	v_lshl_add_u64 v[198:199], v[200:201], 0, v[198:199]
	v_mov_b64_e32 v[200:201], s[4:5]
	v_mad_i64_i32 v[200:201], s[6:7], v190, s66, v[200:201]
	v_lshl_add_u64 v[200:201], v[188:189], 1, v[200:201]
	s_lshl_b32 s44, s12, 2
	s_ashr_i32 s45, s44, 31
	s_waitcnt vmcnt(0)
; __device__ __forceinline__ unsigned cvt_pk_bf16(float lo, float hi) { unsigned r; asm volatile("v_cvt_pk_bf16_f32 %0, %1, %2" : "=v"(r) : "v"(lo), "v"(hi)); return r; }
;     __device__ __forceinline__ void operator()(const f32x4 (&acc)[2][2][4][2], const Unit& u, int wr, int wc, int fr, int fq, const LAS float*) const {
;     ...
;             for (int m = m0; m < m0 + MB; ++m) { const int row = row0 + ai * HALF + m * 16; float ss = 0.f;
;                 float* xr = X + (size_t)row * DM + col0; bf16_t* xb = XB + (size_t)row * ALD + col0;
; #pragma unroll
;                 for (int bj = 0; bj < 2; ++bj) { f32x4 x0 = xo[m][bj][0], x1 = xo[m][bj][1];
;                     if (HB) { x0 += (acc[ai][bj][m][0] + bv[bj][0]) * sv[bj][0]; x1 += (acc[ai][bj][m][1] + bv[bj][1]) * sv[bj][1]; } else { x0 += acc[ai][bj][m][0]; x1 += acc[ai][bj][m][1]; }
;                     *(f32x4*)(xr + bj * HALF) = x0; *(f32x4*)(xr + bj * HALF + 4) = x1;
;                     ss += (x0[0] * x0[0] + x0[1] * x0[1]) + (x0[2] * x0[2] + x0[3] * x0[3]) + (x1[0] * x1[0] + x1[1] * x1[1]) + (x1[2] * x1[2] + x1[3] * x1[3]);
;                     u32x4 w; w.x = cvt_pk_bf16(x0[0], x0[1]); w.y = cvt_pk_bf16(x0[2], x0[3]); w.z = cvt_pk_bf16(x1[0], x1[1]); w.w = cvt_pk_bf16(x1[2], x1[3]);
;                     if (feeds) *(u32x4*)(xb + bj * HALF) = w; }
;                 ss += __shfl_xor(ss, 16); ss += __shfl_xor(ss, 32);
;                 if (fq == 0 && feeds) part[(size_t)row * NPART + u.pn * 4 + wc] = ss; }
	v_pk_add_f32 v[156:157], v[156:157], v[92:93]
	v_pk_add_f32 v[162:163], v[162:163], v[102:103]
	v_pk_add_f32 v[160:161], v[160:161], v[100:101]
	v_pk_add_f32 v[158:159], v[158:159], v[94:95]
	v_pk_add_f32 v[148:149], v[148:149], v[76:77]
	v_pk_fma_f32 v[156:157], v[88:89], v[156:157], v[216:217]
	v_pk_fma_f32 v[162:163], v[98:99], v[162:163], v[222:223]
	v_pk_fma_f32 v[160:161], v[96:97], v[160:161], v[220:221]
	v_mul_f32_e32 v216, v163, v163
	v_mul_f32_e32 v215, v161, v161
	v_fmac_f32_e32 v215, v160, v160
	v_fmac_f32_e32 v216, v162, v162
	v_pk_add_f32 v[154:155], v[154:155], v[86:87]
	v_pk_add_f32 v[152:153], v[152:153], v[84:85]
	v_add_f32_e32 v215, v215, v216
	v_mul_f32_e32 v216, v157, v157
	v_pk_fma_f32 v[154:155], v[82:83], v[154:155], v[230:231]
	v_pk_fma_f32 v[152:153], v[80:81], v[152:153], v[228:229]
	v_pk_fma_f32 v[158:159], v[90:91], v[158:159], v[218:219]
	global_store_dwordx4 v[198:199], v[160:163], off
	global_store_dwordx4 v[198:199], v[156:159], off offset:16
	v_fmac_f32_e32 v216, v156, v156
	v_cvt_pk_bf16_f32 v160, v160, v161
	v_cvt_pk_bf16_f32 v161, v162, v163
	v_cvt_pk_bf16_f32 v162, v156, v157
	v_pk_fma_f32 v[148:149], v[68:69], v[148:149], v[224:225]
	v_mul_f32_e32 v156, v153, v153
	v_mul_f32_e32 v157, v155, v155
	v_fmac_f32_e32 v156, v152, v152
	v_fmac_f32_e32 v157, v154, v154
	v_pk_add_f32 v[150:151], v[150:151], v[78:79]
	v_add_f32_e32 v156, v156, v157
	v_mul_f32_e32 v157, v149, v149
	v_cvt_pk_bf16_f32 v163, v158, v159
	global_store_dwordx4 v[200:201], v[160:163], off
	v_pk_fma_f32 v[150:151], v[70:71], v[150:151], v[226:227]
	global_store_dwordx4 v[198:199], v[152:155], off offset:512
	global_store_dwordx4 v[198:199], v[148:151], off offset:528
	v_fmac_f32_e32 v157, v148, v148
	v_cvt_pk_bf16_f32 v152, v152, v153
	v_cvt_pk_bf16_f32 v153, v154, v155
	v_cvt_pk_bf16_f32 v154, v148, v149
	v_add_f32_e32 v215, v215, v216
	v_and_b32_e32 v149, 64, v239
	v_mul_f32_e32 v216, v159, v159
	v_add_f32_e32 v156, v156, v157
	v_mul_f32_e32 v157, v151, v151
	v_xor_b32_e32 v148, 16, v239
	v_add_u32_e32 v149, 64, v149
	v_fmac_f32_e32 v216, v158, v158
	v_fmac_f32_e32 v157, v150, v150
	v_cmp_lt_i32_e32 vcc, v148, v149
	v_add_f32_e32 v215, v216, v215
	v_add_f32_e32 v156, v157, v156
	v_cndmask_b32_e32 v148, v239, v148, vcc
	v_add_f32_e32 v156, v215, v156
	v_cvt_pk_bf16_f32 v155, v150, v151
	global_store_dwordx4 v[200:201], v[152:155], off offset:256
	v_xor_b32_e32 v150, 32, v239
	v_cmp_lt_i32_e32 vcc, v150, v149
	v_lshlrev_b32_e32 v154, 2, v148
	v_mov_b32_e32 v148, v156
	s_nop 1
	v_permlane16_swap_b32_e32 v148, v156
	v_cndmask_b32_e32 v149, v239, v150, vcc
	v_lshlrev_b32_e32 v155, 2, v149
	s_waitcnt lgkmcnt(0)
	v_add_f32_e32 v148, v156, v148
	v_mov_b32_e32 v149, v148
	s_nop 1
	v_permlane32_swap_b32_e32 v149, v148
	s_and_saveexec_b64 s[50:51], s[38:39]
	s_cbranch_execz .LBB0_172
	v_lshlrev_b64 v[150:151], 7, v[190:191]
	v_lshl_add_u64 v[150:151], s[94:95], 0, v[150:151]
	v_lshl_add_u64 v[150:151], s[44:45], 2, v[150:151]
	s_lshl_b32 s30, s58, 2
	v_lshl_add_u64 v[150:151], v[150:151], 0, s[30:31]
	s_waitcnt lgkmcnt(0)
	v_add_f32_e32 v148, v148, v149
	global_store_dword v[150:151], v148, off
.LBB0_172:
	s_or_b64 exec, exec, s[50:51]
	v_pk_add_f32 v[146:147], v[146:147], v[102:103]
	v_pk_add_f32 v[144:145], v[144:145], v[100:101]
	v_pk_fma_f32 v[146:147], v[98:99], v[146:147], v[178:179]
	v_pk_fma_f32 v[144:145], v[96:97], v[144:145], v[176:177]
	v_pk_add_f32 v[140:141], v[140:141], v[92:93]
	v_mul_f32_e32 v152, v145, v145
	v_mul_f32_e32 v153, v147, v147
	s_waitcnt lgkmcnt(0)
	v_lshl_add_u64 v[148:149], s[82:83], 0, v[210:211]
	v_pk_fma_f32 v[140:141], v[88:89], v[140:141], v[172:173]
	v_fmac_f32_e32 v152, v144, v144
	v_fmac_f32_e32 v153, v146, v146
	v_pk_add_f32 v[134:135], v[134:135], v[86:87]
	v_pk_add_f32 v[132:133], v[132:133], v[84:85]
	v_lshl_add_u64 v[148:149], v[188:189], 2, v[148:149]
	v_pk_add_f32 v[142:143], v[142:143], v[94:95]
	v_add_f32_e32 v152, v152, v153
	v_mul_f32_e32 v153, v141, v141
	v_pk_fma_f32 v[134:135], v[82:83], v[134:135], v[170:171]
	v_pk_fma_f32 v[132:133], v[80:81], v[132:133], v[168:169]
	v_pk_add_f32 v[128:129], v[128:129], v[76:77]
	v_pk_fma_f32 v[142:143], v[90:91], v[142:143], v[174:175]
	global_store_dwordx4 v[148:149], v[144:147], off
	global_store_dwordx4 v[148:149], v[140:143], off offset:16
	v_fmac_f32_e32 v153, v140, v140
	v_cvt_pk_bf16_f32 v144, v144, v145
	v_cvt_pk_bf16_f32 v145, v146, v147
	v_cvt_pk_bf16_f32 v146, v140, v141
	v_add_f32_e32 v152, v152, v153
	v_pk_fma_f32 v[140:141], v[68:69], v[128:129], v[164:165]
	v_mul_f32_e32 v128, v133, v133
	v_mul_f32_e32 v129, v135, v135
	v_fmac_f32_e32 v128, v132, v132
	v_fmac_f32_e32 v129, v134, v134
	v_mul_f32_e32 v153, v143, v143
	v_pk_add_f32 v[130:131], v[130:131], v[78:79]
	v_add_f32_e32 v128, v128, v129
	v_mul_f32_e32 v129, v141, v141
	v_fmac_f32_e32 v153, v142, v142
	v_cvt_pk_bf16_f32 v147, v142, v143
	v_pk_fma_f32 v[142:143], v[70:71], v[130:131], v[166:167]
	v_fmac_f32_e32 v129, v140, v140
	v_add_f32_e32 v128, v128, v129
	v_mul_f32_e32 v129, v143, v143
	v_fmac_f32_e32 v129, v142, v142
	v_add_f32_e32 v152, v153, v152
	v_add_f32_e32 v128, v129, v128
	v_add_f32_e32 v128, v152, v128
	v_mov_b32_e32 v129, v128
	s_nop 1
	v_permlane16_swap_b32_e32 v129, v128
	v_mov_b64_e32 v[150:151], s[4:5]
	v_mad_i64_i32 v[150:151], s[6:7], v208, s66, v[150:151]
	v_lshl_add_u64 v[150:151], v[188:189], 1, v[150:151]
	s_waitcnt lgkmcnt(0)
	v_add_f32_e32 v128, v128, v129
	v_mov_b32_e32 v129, v128
	s_nop 1
	v_permlane32_swap_b32_e32 v129, v128
	global_store_dwordx4 v[150:151], v[144:147], off
	global_store_dwordx4 v[148:149], v[132:135], off offset:512
	global_store_dwordx4 v[148:149], v[140:143], off offset:528
	v_cvt_pk_bf16_f32 v130, v132, v133
	v_cvt_pk_bf16_f32 v131, v134, v135
	s_nop 0
	v_cvt_pk_bf16_f32 v132, v140, v141
	v_cvt_pk_bf16_f32 v133, v142, v143
	global_store_dwordx4 v[150:151], v[130:133], off offset:256
	s_and_saveexec_b64 s[50:51], s[38:39]
	s_cbranch_execz .LBB0_174
	v_lshlrev_b64 v[130:131], 7, v[208:209]
	v_lshl_add_u64 v[130:131], s[94:95], 0, v[130:131]
	v_lshl_add_u64 v[130:131], s[44:45], 2, v[130:131]
	s_lshl_b32 s30, s58, 2
	v_lshl_add_u64 v[130:131], v[130:131], 0, s[30:31]
	s_waitcnt lgkmcnt(0)
	v_add_f32_e32 v128, v128, v129
	global_store_dword v[130:131], v128, off
.LBB0_174:
	s_or_b64 exec, exec, s[50:51]
	v_or_b32_e32 v150, 32, v190
	v_ashrrev_i32_e32 v151, 31, v150
	v_lshlrev_b64 v[172:173], 13, v[150:151]
	s_waitcnt lgkmcnt(0)
	v_lshl_add_u64 v[128:129], v[206:207], 0, v[172:173]
	global_load_dwordx4 v[156:159], v[128:129], off
	global_load_dwordx4 v[160:163], v[128:129], off offset:16
	global_load_dwordx4 v[164:167], v[128:129], off offset:512
	global_load_dwordx4 v[168:171], v[128:129], off offset:528
	v_or_b32_e32 v148, 48, v190
	v_ashrrev_i32_e32 v149, 31, v148
	v_lshlrev_b64 v[152:153], 13, v[148:149]
	v_lshl_add_u64 v[132:133], v[206:207], 0, v[152:153]
	global_load_dwordx4 v[140:143], v[132:133], off offset:16
	global_load_dwordx4 v[144:147], v[132:133], off
	global_load_dwordx4 v[128:131], v[132:133], off offset:528
	s_nop 0
	global_load_dwordx4 v[132:135], v[132:133], off offset:512
	v_mov_b64_e32 v[174:175], s[4:5]
	v_pk_add_f32 v[200:201], v[112:113], v[76:77]
	v_mad_i64_i32 v[112:113], s[6:7], v150, s66, v[174:175]
	v_pk_add_f32 v[126:127], v[126:127], v[102:103]
	v_pk_add_f32 v[124:125], v[124:125], v[100:101]
	v_pk_add_f32 v[122:123], v[122:123], v[94:95]
	v_pk_add_f32 v[120:121], v[120:121], v[92:93]
	v_pk_add_f32 v[176:177], v[118:119], v[86:87]
	v_pk_add_f32 v[178:179], v[116:117], v[84:85]
	v_lshl_add_u64 v[174:175], v[188:189], 1, v[112:113]
	v_lshl_add_u64 v[112:113], s[82:83], 0, v[172:173]
	v_pk_add_f32 v[198:199], v[114:115], v[78:79]
	v_lshl_add_u64 v[172:173], v[188:189], 2, v[112:113]
	s_waitcnt vmcnt(7)
	v_pk_fma_f32 v[114:115], v[98:99], v[126:127], v[158:159]
	v_pk_fma_f32 v[112:113], v[96:97], v[124:125], v[156:157]
	s_waitcnt vmcnt(6)
	v_pk_fma_f32 v[118:119], v[90:91], v[122:123], v[162:163]
	v_pk_fma_f32 v[116:117], v[88:89], v[120:121], v[160:161]
	s_waitcnt vmcnt(5)
	v_pk_fma_f32 v[122:123], v[82:83], v[176:177], v[166:167]
	v_pk_fma_f32 v[120:121], v[80:81], v[178:179], v[164:165]
	s_waitcnt vmcnt(4)
	v_pk_fma_f32 v[124:125], v[68:69], v[200:201], v[168:169]
	global_store_dwordx4 v[172:173], v[112:115], off
	global_store_dwordx4 v[172:173], v[116:119], off offset:16
	v_mul_f32_e32 v160, v113, v113
	v_mul_f32_e32 v161, v115, v115
	v_cvt_pk_bf16_f32 v156, v112, v113
	v_cvt_pk_bf16_f32 v157, v114, v115
	v_mul_f32_e32 v113, v121, v121
	v_mul_f32_e32 v115, v123, v123
	v_pk_fma_f32 v[126:127], v[70:71], v[198:199], v[170:171]
	v_mul_f32_e32 v162, v117, v117
	v_cvt_pk_bf16_f32 v158, v116, v117
	v_mul_f32_e32 v117, v125, v125
	v_fmac_f32_e32 v160, v112, v112
	v_fmac_f32_e32 v161, v114, v114
	v_fmac_f32_e32 v113, v120, v120
	v_fmac_f32_e32 v115, v122, v122
	v_mul_f32_e32 v163, v119, v119
	v_cvt_pk_bf16_f32 v159, v118, v119
	v_mul_f32_e32 v119, v127, v127
	v_fmac_f32_e32 v162, v116, v116
	v_fmac_f32_e32 v117, v124, v124
	v_add_f32_e32 v112, v160, v161
	v_add_f32_e32 v113, v113, v115
	v_fmac_f32_e32 v163, v118, v118
	v_fmac_f32_e32 v119, v126, v126
	v_add_f32_e32 v112, v112, v162
	v_add_f32_e32 v113, v113, v117
	v_add_f32_e32 v112, v163, v112
	v_add_f32_e32 v113, v119, v113
	v_add_f32_e32 v112, v112, v113
	v_mov_b32_e32 v113, v112
	s_nop 1
	v_permlane16_swap_b32_e32 v113, v112
	global_store_dwordx4 v[174:175], v[156:159], off
	global_store_dwordx4 v[172:173], v[120:123], off offset:512
	global_store_dwordx4 v[172:173], v[124:127], off offset:528
	v_cvt_pk_bf16_f32 v114, v120, v121
	v_cvt_pk_bf16_f32 v115, v122, v123
	v_cvt_pk_bf16_f32 v116, v124, v125
	s_waitcnt lgkmcnt(0)
	v_add_f32_e32 v112, v112, v113
	v_mov_b32_e32 v113, v112
	s_nop 1
	v_permlane32_swap_b32_e32 v113, v112
	v_cvt_pk_bf16_f32 v117, v126, v127
	global_store_dwordx4 v[174:175], v[114:117], off offset:256
	s_and_saveexec_b64 s[50:51], s[38:39]
	s_cbranch_execz .LBB0_176
	v_lshlrev_b64 v[114:115], 7, v[150:151]
	v_lshl_add_u64 v[114:115], s[94:95], 0, v[114:115]
	v_lshl_add_u64 v[114:115], s[44:45], 2, v[114:115]
	s_lshl_b32 s30, s58, 2
	v_lshl_add_u64 v[114:115], v[114:115], 0, s[30:31]
	s_waitcnt lgkmcnt(0)
	v_add_f32_e32 v112, v112, v113
	global_store_dword v[114:115], v112, off
.LBB0_176:
	s_or_b64 exec, exec, s[50:51]
	v_pk_add_f32 v[110:111], v[110:111], v[102:103]
	v_pk_add_f32 v[108:109], v[108:109], v[100:101]
	s_waitcnt vmcnt(8)
	v_pk_fma_f32 v[110:111], v[98:99], v[110:111], v[146:147]
	v_pk_fma_f32 v[108:109], v[96:97], v[108:109], v[144:145]
	v_pk_add_f32 v[104:105], v[104:105], v[92:93]
	v_mul_f32_e32 v116, v109, v109
	v_mul_f32_e32 v117, v111, v111
	s_waitcnt lgkmcnt(0)
	v_lshl_add_u64 v[112:113], s[82:83], 0, v[152:153]
	v_pk_fma_f32 v[104:105], v[88:89], v[104:105], v[140:141]
	v_fmac_f32_e32 v116, v108, v108
	v_fmac_f32_e32 v117, v110, v110
	v_pk_add_f32 v[74:75], v[74:75], v[86:87]
	v_pk_add_f32 v[72:73], v[72:73], v[84:85]
	v_lshl_add_u64 v[112:113], v[188:189], 2, v[112:113]
	v_pk_add_f32 v[106:107], v[106:107], v[94:95]
	v_add_f32_e32 v116, v116, v117
	v_mul_f32_e32 v117, v105, v105
	s_waitcnt vmcnt(6)
	v_pk_fma_f32 v[74:75], v[82:83], v[74:75], v[134:135]
	v_pk_fma_f32 v[72:73], v[80:81], v[72:73], v[132:133]
	v_pk_add_f32 v[64:65], v[64:65], v[76:77]
	v_pk_fma_f32 v[106:107], v[90:91], v[106:107], v[142:143]
	global_store_dwordx4 v[112:113], v[108:111], off
	global_store_dwordx4 v[112:113], v[104:107], off offset:16
	v_fmac_f32_e32 v117, v104, v104
	v_cvt_pk_bf16_f32 v108, v108, v109
	v_cvt_pk_bf16_f32 v109, v110, v111
	v_cvt_pk_bf16_f32 v110, v104, v105
	v_add_f32_e32 v116, v116, v117
	v_pk_fma_f32 v[104:105], v[68:69], v[64:65], v[128:129]
	v_mul_f32_e32 v64, v73, v73
	v_mul_f32_e32 v65, v75, v75
	v_fmac_f32_e32 v64, v72, v72
	v_fmac_f32_e32 v65, v74, v74
	v_mul_f32_e32 v117, v107, v107
	v_pk_add_f32 v[66:67], v[66:67], v[78:79]
	v_add_f32_e32 v64, v64, v65
	v_mul_f32_e32 v65, v105, v105
	v_fmac_f32_e32 v117, v106, v106
	v_cvt_pk_bf16_f32 v111, v106, v107
	v_pk_fma_f32 v[106:107], v[70:71], v[66:67], v[130:131]
	v_fmac_f32_e32 v65, v104, v104
	v_add_f32_e32 v64, v64, v65
	v_mul_f32_e32 v65, v107, v107
	v_fmac_f32_e32 v65, v106, v106
	v_add_f32_e32 v116, v117, v116
	v_add_f32_e32 v64, v65, v64
	v_add_f32_e32 v64, v116, v64
	v_mov_b32_e32 v65, v64
	s_nop 1
	v_permlane16_swap_b32_e32 v65, v64
	v_mov_b64_e32 v[114:115], s[4:5]
	v_mad_i64_i32 v[114:115], s[6:7], v148, s66, v[114:115]
	v_lshl_add_u64 v[114:115], v[188:189], 1, v[114:115]
	s_waitcnt lgkmcnt(0)
	v_add_f32_e32 v64, v64, v65
	v_mov_b32_e32 v65, v64
	s_nop 1
	v_permlane32_swap_b32_e32 v65, v64
	global_store_dwordx4 v[114:115], v[108:111], off
	global_store_dwordx4 v[112:113], v[72:75], off offset:512
	global_store_dwordx4 v[112:113], v[104:107], off offset:528
	s_nop 0
	v_cvt_pk_bf16_f32 v72, v72, v73
	v_cvt_pk_bf16_f32 v73, v74, v75
	v_cvt_pk_bf16_f32 v74, v104, v105
	v_cvt_pk_bf16_f32 v75, v106, v107
	global_store_dwordx4 v[114:115], v[72:75], off offset:256
	s_and_saveexec_b64 s[50:51], s[38:39]
	s_cbranch_execz .LBB0_178
	v_lshlrev_b64 v[66:67], 7, v[148:149]
	v_lshl_add_u64 v[66:67], s[94:95], 0, v[66:67]
	v_lshl_add_u64 v[66:67], s[44:45], 2, v[66:67]
	s_lshl_b32 s30, s58, 2
	v_lshl_add_u64 v[66:67], v[66:67], 0, s[30:31]
	s_waitcnt lgkmcnt(0)
	v_add_f32_e32 v64, v64, v65
	global_store_dword v[66:67], v64, off
.LBB0_178:
	s_or_b64 exec, exec, s[50:51]
	v_add_u32_e32 v114, 0x80, v190
	v_ashrrev_i32_e32 v115, 31, v114
	v_lshlrev_b64 v[134:135], 13, v[114:115]
	s_waitcnt lgkmcnt(0)
	v_lshl_add_u64 v[64:65], v[206:207], 0, v[134:135]
	global_load_dwordx4 v[118:121], v[64:65], off
	global_load_dwordx4 v[122:125], v[64:65], off offset:16
	global_load_dwordx4 v[126:129], v[64:65], off offset:512
	global_load_dwordx4 v[130:133], v[64:65], off offset:528
	v_add_u32_e32 v112, 0x90, v190
	v_ashrrev_i32_e32 v113, 31, v112
	v_lshlrev_b64 v[116:117], 13, v[112:113]
	v_lshl_add_u64 v[72:73], v[206:207], 0, v[116:117]
	global_load_dwordx4 v[104:107], v[72:73], off offset:16
	global_load_dwordx4 v[108:111], v[72:73], off
	global_load_dwordx4 v[64:67], v[72:73], off offset:528
	s_nop 0
	global_load_dwordx4 v[72:75], v[72:73], off offset:512
	v_mov_b64_e32 v[140:141], s[4:5]
	v_pk_add_f32 v[148:149], v[48:49], v[76:77]
	v_mad_i64_i32 v[48:49], s[6:7], v114, s66, v[140:141]
	v_pk_add_f32 v[62:63], v[62:63], v[102:103]
	v_pk_add_f32 v[60:61], v[60:61], v[100:101]
	v_pk_add_f32 v[58:59], v[58:59], v[94:95]
	v_pk_add_f32 v[56:57], v[56:57], v[92:93]
	v_pk_add_f32 v[142:143], v[54:55], v[86:87]
	v_pk_add_f32 v[144:145], v[52:53], v[84:85]
	v_lshl_add_u64 v[140:141], v[188:189], 1, v[48:49]
	v_lshl_add_u64 v[48:49], s[82:83], 0, v[134:135]
	v_pk_add_f32 v[146:147], v[50:51], v[78:79]
	v_lshl_add_u64 v[134:135], v[188:189], 2, v[48:49]
	s_waitcnt vmcnt(7)
	v_pk_fma_f32 v[50:51], v[98:99], v[62:63], v[120:121]
	v_pk_fma_f32 v[48:49], v[96:97], v[60:61], v[118:119]
	s_waitcnt vmcnt(6)
	v_pk_fma_f32 v[54:55], v[90:91], v[58:59], v[124:125]
	v_pk_fma_f32 v[52:53], v[88:89], v[56:57], v[122:123]
	s_waitcnt vmcnt(5)
	v_pk_fma_f32 v[58:59], v[82:83], v[142:143], v[128:129]
	v_pk_fma_f32 v[56:57], v[80:81], v[144:145], v[126:127]
	s_waitcnt vmcnt(4)
	v_pk_fma_f32 v[60:61], v[68:69], v[148:149], v[130:131]
	global_store_dwordx4 v[134:135], v[48:51], off
	global_store_dwordx4 v[134:135], v[52:55], off offset:16
	v_mul_f32_e32 v122, v49, v49
	v_mul_f32_e32 v123, v51, v51
	v_cvt_pk_bf16_f32 v118, v48, v49
	v_cvt_pk_bf16_f32 v119, v50, v51
	v_mul_f32_e32 v49, v57, v57
	v_mul_f32_e32 v51, v59, v59
	v_pk_fma_f32 v[62:63], v[70:71], v[146:147], v[132:133]
	v_mul_f32_e32 v124, v53, v53
	v_cvt_pk_bf16_f32 v120, v52, v53
	v_mul_f32_e32 v53, v61, v61
	v_fmac_f32_e32 v122, v48, v48
	v_fmac_f32_e32 v123, v50, v50
	v_fmac_f32_e32 v49, v56, v56
	v_fmac_f32_e32 v51, v58, v58
	v_mul_f32_e32 v125, v55, v55
	v_cvt_pk_bf16_f32 v121, v54, v55
	v_mul_f32_e32 v55, v63, v63
	v_fmac_f32_e32 v124, v52, v52
	v_fmac_f32_e32 v53, v60, v60
	v_add_f32_e32 v48, v122, v123
	v_add_f32_e32 v49, v49, v51
	v_fmac_f32_e32 v125, v54, v54
	v_fmac_f32_e32 v55, v62, v62
	v_add_f32_e32 v48, v48, v124
	v_add_f32_e32 v49, v49, v53
	v_add_f32_e32 v48, v125, v48
	v_add_f32_e32 v49, v55, v49
	v_add_f32_e32 v48, v48, v49
	v_mov_b32_e32 v49, v48
	s_nop 1
	v_permlane16_swap_b32_e32 v49, v48
	global_store_dwordx4 v[140:141], v[118:121], off
	global_store_dwordx4 v[134:135], v[56:59], off offset:512
	global_store_dwordx4 v[134:135], v[60:63], off offset:528
	v_cvt_pk_bf16_f32 v50, v56, v57
	v_cvt_pk_bf16_f32 v51, v58, v59
	v_cvt_pk_bf16_f32 v52, v60, v61
	s_waitcnt lgkmcnt(0)
	v_add_f32_e32 v48, v48, v49
	v_mov_b32_e32 v49, v48
	s_nop 1
	v_permlane32_swap_b32_e32 v49, v48
	v_cvt_pk_bf16_f32 v53, v62, v63
	global_store_dwordx4 v[140:141], v[50:53], off offset:256
	s_and_saveexec_b64 s[50:51], s[38:39]
	s_cbranch_execz .LBB0_180
	v_lshlrev_b64 v[50:51], 7, v[114:115]
	v_lshl_add_u64 v[50:51], s[94:95], 0, v[50:51]
	v_lshl_add_u64 v[50:51], s[44:45], 2, v[50:51]
	s_lshl_b32 s30, s58, 2
	v_lshl_add_u64 v[50:51], v[50:51], 0, s[30:31]
	s_waitcnt lgkmcnt(0)
	v_add_f32_e32 v48, v48, v49
	global_store_dword v[50:51], v48, off
.LBB0_180:
	s_or_b64 exec, exec, s[50:51]
	v_pk_add_f32 v[46:47], v[46:47], v[102:103]
	v_pk_add_f32 v[44:45], v[44:45], v[100:101]
	s_waitcnt vmcnt(8)
	v_pk_fma_f32 v[46:47], v[98:99], v[46:47], v[110:111]
	v_pk_fma_f32 v[44:45], v[96:97], v[44:45], v[108:109]
	v_pk_add_f32 v[40:41], v[40:41], v[92:93]
	v_mul_f32_e32 v52, v45, v45
	v_mul_f32_e32 v53, v47, v47
	s_waitcnt lgkmcnt(0)
	v_lshl_add_u64 v[48:49], s[82:83], 0, v[116:117]
	v_pk_fma_f32 v[40:41], v[88:89], v[40:41], v[104:105]
	v_fmac_f32_e32 v52, v44, v44
	v_fmac_f32_e32 v53, v46, v46
	v_pk_add_f32 v[38:39], v[38:39], v[86:87]
	v_pk_add_f32 v[36:37], v[36:37], v[84:85]
	v_lshl_add_u64 v[48:49], v[188:189], 2, v[48:49]
	v_pk_add_f32 v[42:43], v[42:43], v[94:95]
	v_add_f32_e32 v52, v52, v53
	v_mul_f32_e32 v53, v41, v41
	s_waitcnt vmcnt(6)
	v_pk_fma_f32 v[38:39], v[82:83], v[38:39], v[74:75]
	v_pk_fma_f32 v[36:37], v[80:81], v[36:37], v[72:73]
	v_pk_add_f32 v[32:33], v[32:33], v[76:77]
	v_pk_fma_f32 v[42:43], v[90:91], v[42:43], v[106:107]
	global_store_dwordx4 v[48:49], v[44:47], off
	global_store_dwordx4 v[48:49], v[40:43], off offset:16
	v_fmac_f32_e32 v53, v40, v40
	v_cvt_pk_bf16_f32 v44, v44, v45
	v_cvt_pk_bf16_f32 v45, v46, v47
	v_cvt_pk_bf16_f32 v46, v40, v41
	v_add_f32_e32 v52, v52, v53
	v_pk_fma_f32 v[40:41], v[68:69], v[32:33], v[64:65]
	v_mul_f32_e32 v32, v37, v37
	v_mul_f32_e32 v33, v39, v39
	v_fmac_f32_e32 v32, v36, v36
	v_fmac_f32_e32 v33, v38, v38
	v_mul_f32_e32 v53, v43, v43
	v_pk_add_f32 v[34:35], v[34:35], v[78:79]
	v_add_f32_e32 v32, v32, v33
	v_mul_f32_e32 v33, v41, v41
	v_fmac_f32_e32 v53, v42, v42
	v_cvt_pk_bf16_f32 v47, v42, v43
	v_pk_fma_f32 v[42:43], v[70:71], v[34:35], v[66:67]
	v_fmac_f32_e32 v33, v40, v40
	v_add_f32_e32 v32, v32, v33
	v_mul_f32_e32 v33, v43, v43
	v_fmac_f32_e32 v33, v42, v42
	v_add_f32_e32 v52, v53, v52
	v_add_f32_e32 v32, v33, v32
	v_add_f32_e32 v32, v52, v32
	v_mov_b32_e32 v33, v32
	s_nop 1
	v_permlane16_swap_b32_e32 v33, v32
	v_mov_b64_e32 v[50:51], s[4:5]
	v_mad_i64_i32 v[50:51], s[6:7], v112, s66, v[50:51]
	v_lshl_add_u64 v[50:51], v[188:189], 1, v[50:51]
	s_waitcnt lgkmcnt(0)
	v_add_f32_e32 v32, v32, v33
	v_mov_b32_e32 v33, v32
	s_nop 1
	v_permlane32_swap_b32_e32 v33, v32
	global_store_dwordx4 v[50:51], v[44:47], off
	global_store_dwordx4 v[48:49], v[36:39], off offset:512
	global_store_dwordx4 v[48:49], v[40:43], off offset:528
	v_cvt_pk_bf16_f32 v34, v36, v37
	v_cvt_pk_bf16_f32 v35, v38, v39
	s_nop 0
	v_cvt_pk_bf16_f32 v36, v40, v41
	v_cvt_pk_bf16_f32 v37, v42, v43
	global_store_dwordx4 v[50:51], v[34:37], off offset:256
	s_and_saveexec_b64 s[50:51], s[38:39]
	s_cbranch_execz .LBB0_182
	v_lshlrev_b64 v[34:35], 7, v[112:113]
	v_lshl_add_u64 v[34:35], s[94:95], 0, v[34:35]
	v_lshl_add_u64 v[34:35], s[44:45], 2, v[34:35]
	s_lshl_b32 s30, s58, 2
	v_lshl_add_u64 v[34:35], v[34:35], 0, s[30:31]
	s_waitcnt lgkmcnt(0)
	v_add_f32_e32 v32, v32, v33
	global_store_dword v[34:35], v32, off
.LBB0_182:
	s_or_b64 exec, exec, s[50:51]
	v_add_u32_e32 v50, 0xa0, v190
	v_ashrrev_i32_e32 v51, 31, v50
	v_lshlrev_b64 v[66:67], 13, v[50:51]
	s_waitcnt lgkmcnt(0)
	v_lshl_add_u64 v[32:33], v[206:207], 0, v[66:67]
	global_load_dwordx4 v[54:57], v[32:33], off
	global_load_dwordx4 v[58:61], v[32:33], off offset:16
	global_load_dwordx4 v[62:65], v[32:33], off offset:512
	global_load_dwordx4 v[72:75], v[32:33], off offset:528
	v_add_u32_e32 v48, 0xb0, v190
	v_ashrrev_i32_e32 v49, 31, v48
	v_lshlrev_b64 v[52:53], 13, v[48:49]
	v_lshl_add_u64 v[36:37], v[206:207], 0, v[52:53]
	global_load_dwordx4 v[40:43], v[36:37], off offset:16
	global_load_dwordx4 v[44:47], v[36:37], off
	global_load_dwordx4 v[32:35], v[36:37], off offset:528
	s_nop 0
	global_load_dwordx4 v[36:39], v[36:37], off offset:512
	v_mov_b64_e32 v[104:105], s[4:5]
	v_pk_add_f32 v[112:113], v[16:17], v[76:77]
	v_mad_i64_i32 v[16:17], s[6:7], v50, s66, v[104:105]
	v_pk_add_f32 v[30:31], v[30:31], v[102:103]
	v_pk_add_f32 v[28:29], v[28:29], v[100:101]
	v_pk_add_f32 v[26:27], v[26:27], v[94:95]
	v_pk_add_f32 v[24:25], v[24:25], v[92:93]
	v_pk_add_f32 v[106:107], v[22:23], v[86:87]
	v_pk_add_f32 v[108:109], v[20:21], v[84:85]
	v_lshl_add_u64 v[104:105], v[188:189], 1, v[16:17]
	v_lshl_add_u64 v[16:17], s[82:83], 0, v[66:67]
	v_pk_add_f32 v[110:111], v[18:19], v[78:79]
	v_lshl_add_u64 v[66:67], v[188:189], 2, v[16:17]
	s_waitcnt vmcnt(7)
	v_pk_fma_f32 v[18:19], v[98:99], v[30:31], v[56:57]
	v_pk_fma_f32 v[16:17], v[96:97], v[28:29], v[54:55]
	s_waitcnt vmcnt(6)
	v_pk_fma_f32 v[22:23], v[90:91], v[26:27], v[60:61]
	v_pk_fma_f32 v[20:21], v[88:89], v[24:25], v[58:59]
	s_waitcnt vmcnt(5)
	v_pk_fma_f32 v[26:27], v[82:83], v[106:107], v[64:65]
	v_pk_fma_f32 v[24:25], v[80:81], v[108:109], v[62:63]
	s_waitcnt vmcnt(4)
	v_pk_fma_f32 v[28:29], v[68:69], v[112:113], v[72:73]
	global_store_dwordx4 v[66:67], v[16:19], off
	global_store_dwordx4 v[66:67], v[20:23], off offset:16
	v_mul_f32_e32 v58, v17, v17
	v_mul_f32_e32 v59, v19, v19
	v_cvt_pk_bf16_f32 v54, v16, v17
	v_cvt_pk_bf16_f32 v55, v18, v19
	v_mul_f32_e32 v17, v25, v25
	v_mul_f32_e32 v19, v27, v27
	v_pk_fma_f32 v[30:31], v[70:71], v[110:111], v[74:75]
	v_mul_f32_e32 v60, v21, v21
	v_cvt_pk_bf16_f32 v56, v20, v21
	v_mul_f32_e32 v21, v29, v29
	v_fmac_f32_e32 v58, v16, v16
	v_fmac_f32_e32 v59, v18, v18
	v_fmac_f32_e32 v17, v24, v24
	v_fmac_f32_e32 v19, v26, v26
	v_mul_f32_e32 v61, v23, v23
	v_cvt_pk_bf16_f32 v57, v22, v23
	v_mul_f32_e32 v23, v31, v31
	v_fmac_f32_e32 v60, v20, v20
	v_fmac_f32_e32 v21, v28, v28
	v_add_f32_e32 v16, v58, v59
	v_add_f32_e32 v17, v17, v19
	v_fmac_f32_e32 v61, v22, v22
	v_fmac_f32_e32 v23, v30, v30
	v_add_f32_e32 v16, v16, v60
	v_add_f32_e32 v17, v17, v21
	v_add_f32_e32 v16, v61, v16
	v_add_f32_e32 v17, v23, v17
	v_add_f32_e32 v16, v16, v17
	v_mov_b32_e32 v17, v16
	s_nop 1
	v_permlane16_swap_b32_e32 v17, v16
	global_store_dwordx4 v[104:105], v[54:57], off
	global_store_dwordx4 v[66:67], v[24:27], off offset:512
	global_store_dwordx4 v[66:67], v[28:31], off offset:528
	v_cvt_pk_bf16_f32 v18, v24, v25
	v_cvt_pk_bf16_f32 v19, v26, v27
	v_cvt_pk_bf16_f32 v20, v28, v29
	s_waitcnt lgkmcnt(0)
	v_add_f32_e32 v16, v16, v17
	v_mov_b32_e32 v17, v16
	s_nop 1
	v_permlane32_swap_b32_e32 v17, v16
	v_cvt_pk_bf16_f32 v21, v30, v31
	global_store_dwordx4 v[104:105], v[18:21], off offset:256
	s_and_saveexec_b64 s[50:51], s[38:39]
	s_cbranch_execz .LBB0_184
	v_lshlrev_b64 v[18:19], 7, v[50:51]
	v_lshl_add_u64 v[18:19], s[94:95], 0, v[18:19]
	v_lshl_add_u64 v[18:19], s[44:45], 2, v[18:19]
	s_lshl_b32 s30, s58, 2
	v_lshl_add_u64 v[18:19], v[18:19], 0, s[30:31]
	s_waitcnt lgkmcnt(0)
	v_add_f32_e32 v16, v16, v17
	global_store_dword v[18:19], v16, off
.LBB0_184:
	s_or_b64 exec, exec, s[50:51]
	v_pk_add_f32 v[14:15], v[14:15], v[102:103]
	v_pk_add_f32 v[12:13], v[12:13], v[100:101]
	s_waitcnt vmcnt(8)
	v_pk_fma_f32 v[14:15], v[98:99], v[14:15], v[46:47]
	v_pk_fma_f32 v[12:13], v[96:97], v[12:13], v[44:45]
	v_pk_add_f32 v[8:9], v[8:9], v[92:93]
	v_mul_f32_e32 v20, v13, v13
	v_mul_f32_e32 v21, v15, v15
	s_waitcnt lgkmcnt(0)
	v_lshl_add_u64 v[16:17], s[82:83], 0, v[52:53]
	v_pk_fma_f32 v[8:9], v[88:89], v[8:9], v[40:41]
	v_fmac_f32_e32 v20, v12, v12
	v_fmac_f32_e32 v21, v14, v14
	v_pk_add_f32 v[6:7], v[6:7], v[86:87]
	v_pk_add_f32 v[4:5], v[4:5], v[84:85]
	v_lshl_add_u64 v[16:17], v[188:189], 2, v[16:17]
	v_pk_add_f32 v[10:11], v[10:11], v[94:95]
	v_add_f32_e32 v20, v20, v21
	v_mul_f32_e32 v21, v9, v9
	s_waitcnt vmcnt(6)
	v_pk_fma_f32 v[6:7], v[82:83], v[6:7], v[38:39]
	v_pk_fma_f32 v[4:5], v[80:81], v[4:5], v[36:37]
	v_pk_add_f32 v[0:1], v[0:1], v[76:77]
	v_pk_fma_f32 v[10:11], v[90:91], v[10:11], v[42:43]
	global_store_dwordx4 v[16:17], v[12:15], off
	global_store_dwordx4 v[16:17], v[8:11], off offset:16
	v_fmac_f32_e32 v21, v8, v8
	v_cvt_pk_bf16_f32 v12, v12, v13
	v_cvt_pk_bf16_f32 v13, v14, v15
	v_cvt_pk_bf16_f32 v14, v8, v9
	v_add_f32_e32 v20, v20, v21
	v_pk_fma_f32 v[8:9], v[68:69], v[0:1], v[32:33]
	v_mul_f32_e32 v0, v5, v5
	v_mul_f32_e32 v1, v7, v7
	v_fmac_f32_e32 v0, v4, v4
	v_fmac_f32_e32 v1, v6, v6
	v_mul_f32_e32 v21, v11, v11
	v_pk_add_f32 v[2:3], v[2:3], v[78:79]
	v_add_f32_e32 v0, v0, v1
	v_mul_f32_e32 v1, v9, v9
	v_fmac_f32_e32 v21, v10, v10
	v_cvt_pk_bf16_f32 v15, v10, v11
	v_pk_fma_f32 v[10:11], v[70:71], v[2:3], v[34:35]
	v_fmac_f32_e32 v1, v8, v8
	v_add_f32_e32 v0, v0, v1
	v_mul_f32_e32 v1, v11, v11
	v_fmac_f32_e32 v1, v10, v10
	v_add_f32_e32 v20, v21, v20
	v_add_f32_e32 v0, v1, v0
	v_add_f32_e32 v0, v20, v0
	v_mov_b32_e32 v1, v0
	s_nop 1
	v_permlane16_swap_b32_e32 v1, v0
	v_mov_b64_e32 v[18:19], s[4:5]
	v_mad_i64_i32 v[18:19], s[6:7], v48, s66, v[18:19]
	v_lshl_add_u64 v[18:19], v[188:189], 1, v[18:19]
	s_waitcnt lgkmcnt(0)
	v_add_f32_e32 v0, v0, v1
	v_mov_b32_e32 v1, v0
	s_nop 1
	v_permlane32_swap_b32_e32 v1, v0
	global_store_dwordx4 v[18:19], v[12:15], off
	global_store_dwordx4 v[16:17], v[4:7], off offset:512
	global_store_dwordx4 v[16:17], v[8:11], off offset:528
	v_cvt_pk_bf16_f32 v2, v4, v5
	v_cvt_pk_bf16_f32 v3, v6, v7
	s_nop 0
	v_cvt_pk_bf16_f32 v4, v8, v9
	v_cvt_pk_bf16_f32 v5, v10, v11
	global_store_dwordx4 v[18:19], v[2:5], off offset:256
	s_and_saveexec_b64 s[50:51], s[38:39]
	s_cbranch_execz .LBB0_157
	v_lshlrev_b64 v[2:3], 7, v[48:49]
	v_lshl_add_u64 v[2:3], s[94:95], 0, v[2:3]
	v_lshl_add_u64 v[2:3], s[44:45], 2, v[2:3]
	s_lshl_b32 s30, s58, 2
	v_lshl_add_u64 v[2:3], v[2:3], 0, s[30:31]
	s_waitcnt lgkmcnt(0)
	v_add_f32_e32 v0, v0, v1
	global_store_dword v[2:3], v0, off
	s_branch .LBB0_157

.LBB0_273:
	s_or_b64 exec, exec, s[44:45]
	s_lshl_b32 s6, s91, 10
	s_and_b32 s6, s6, 0x400
	s_add_i32 s6, s6, 0
	s_add_i32 s6, s6, 0x20000
	v_mov_b32_e32 v167, 1.0
	s_cmp_lt_i32 s12, 16
	s_cselect_b64 s[52:53], -1, 0
	s_cmp_gt_i32 s12, 15
	v_lshl_add_u32 v223, v189, 2, s6
	v_mov_b32_e32 v166, v167
	v_mov_b32_e32 v165, v167
	v_mov_b32_e32 v164, v167
	v_mov_b32_e32 v171, v167
	v_mov_b32_e32 v170, v167
	v_mov_b32_e32 v169, v167
	v_mov_b32_e32 v168, v167
	s_cbranch_scc1 .LBB0_307
	ds_read_b32 v164, v223
	v_and_b32_e32 v166, 64, v239
	v_xor_b32_e32 v165, 16, v239
	v_add_u32_e32 v167, 64, v166
	v_cmp_lt_i32_e32 vcc, v165, v167
	s_nop 1
	v_cndmask_b32_e32 v165, v239, v165, vcc
	s_waitcnt lgkmcnt(0)
	v_pk_mul_f32 v[168:169], v[162:163], v[164:165] op_sel_hi:[1,0]
	v_pk_mul_f32 v[170:171], v[160:161], v[164:165] op_sel_hi:[1,0]
	v_lshlrev_b32_e32 v166, 2, v165
	v_pk_mul_f32 v[182:183], v[158:159], v[164:165] op_sel_hi:[1,0]
	v_pk_mul_f32 v[184:185], v[156:157], v[164:165] op_sel_hi:[1,0]
	v_mul_f32_e32 v165, v171, v171
	v_mul_f32_e32 v169, v169, v169
	v_fmac_f32_e32 v165, v170, v170
	v_fmac_f32_e32 v169, v168, v168
	v_mul_f32_e32 v168, v185, v185
	v_add_f32_e32 v165, v165, v169
	v_fmac_f32_e32 v168, v184, v184
	v_add_f32_e32 v165, v168, v165
	v_mul_f32_e32 v168, v183, v183
	v_fmac_f32_e32 v168, v182, v182
	v_add_f32_e32 v165, v168, v165
	v_mov_b32_e32 v168, v165
	s_nop 1
	v_permlane16_swap_b32_e32 v168, v165
	v_xor_b32_e32 v169, 32, v239
	v_cmp_lt_i32_e32 vcc, v169, v167
	s_waitcnt lgkmcnt(0)
	v_add_f32_e32 v165, v165, v168
	v_cndmask_b32_e32 v167, v239, v169, vcc
	v_lshlrev_b32_e32 v167, 2, v167
	v_mov_b32_e32 v168, v165
	s_nop 1
	v_permlane32_swap_b32_e32 v168, v165
	s_and_saveexec_b64 s[44:45], s[40:41]
	s_cbranch_execz .LBB0_276
	s_waitcnt lgkmcnt(0)
	v_add_f32_e32 v165, v165, v168
	ds_write_b32 v207, v165
.LBB0_276:
	s_or_b64 exec, exec, s[44:45]
	v_mov_b32_e32 v165, v164
	s_waitcnt lgkmcnt(0)
	v_mov_b32_e32 v168, v164
	v_mov_b32_e32 v169, v164
	v_pk_mul_f32 v[170:171], v[154:155], v[168:169]
	v_pk_mul_f32 v[182:183], v[152:153], v[164:165]
	v_pk_mul_f32 v[164:165], v[148:149], v[164:165]
	v_mul_f32_e32 v183, v183, v183
	v_mul_f32_e32 v171, v171, v171
	v_fmac_f32_e32 v183, v182, v182
	v_fmac_f32_e32 v171, v170, v170
	v_mul_f32_e32 v165, v165, v165
	v_pk_mul_f32 v[168:169], v[150:151], v[168:169]
	v_add_f32_e32 v170, v183, v171
	v_fmac_f32_e32 v165, v164, v164
	v_add_f32_e32 v164, v165, v170
	v_mul_f32_e32 v165, v169, v169
	v_fmac_f32_e32 v165, v168, v168
	v_add_f32_e32 v164, v165, v164
	v_mov_b32_e32 v165, v164
	s_nop 1
	v_permlane16_swap_b32_e32 v165, v164
	s_waitcnt lgkmcnt(0)
	v_add_f32_e32 v164, v164, v165
	v_mov_b32_e32 v165, v164
	s_nop 1
	v_permlane32_swap_b32_e32 v165, v164
	s_and_saveexec_b64 s[44:45], s[40:41]
	s_cbranch_execz .LBB0_278
	s_waitcnt lgkmcnt(0)
	v_add_f32_e32 v164, v164, v165
	ds_write_b32 v207, v164 offset:16
.LBB0_278:
	s_or_b64 exec, exec, s[44:45]
	ds_read_b32 v164, v223 offset:64
	s_waitcnt lgkmcnt(0)
	v_pk_mul_f32 v[168:169], v[146:147], v[164:165] op_sel_hi:[1,0]
	v_pk_mul_f32 v[170:171], v[144:145], v[164:165] op_sel_hi:[1,0]
	v_pk_mul_f32 v[182:183], v[142:143], v[164:165] op_sel_hi:[1,0]
	v_pk_mul_f32 v[184:185], v[140:141], v[164:165] op_sel_hi:[1,0]
	v_mul_f32_e32 v165, v171, v171
	v_mul_f32_e32 v169, v169, v169
	v_fmac_f32_e32 v165, v170, v170
	v_fmac_f32_e32 v169, v168, v168
	v_mul_f32_e32 v168, v185, v185
	v_add_f32_e32 v165, v165, v169
	v_fmac_f32_e32 v168, v184, v184
	v_add_f32_e32 v165, v168, v165
	v_mul_f32_e32 v168, v183, v183
	v_fmac_f32_e32 v168, v182, v182
	v_add_f32_e32 v165, v168, v165
	v_mov_b32_e32 v168, v165
	s_nop 1
	v_permlane16_swap_b32_e32 v168, v165
	s_waitcnt lgkmcnt(0)
	v_add_f32_e32 v165, v165, v168
	v_mov_b32_e32 v168, v165
	s_nop 1
	v_permlane32_swap_b32_e32 v168, v165
	s_and_saveexec_b64 s[44:45], s[40:41]
	s_cbranch_execz .LBB0_280
	s_waitcnt lgkmcnt(0)
	v_add_f32_e32 v165, v165, v168
	ds_write_b32 v209, v165
.LBB0_280:
	s_or_b64 exec, exec, s[44:45]
	v_mov_b32_e32 v165, v164
	s_waitcnt lgkmcnt(0)
	v_mov_b32_e32 v168, v164
	v_mov_b32_e32 v169, v164
	v_pk_mul_f32 v[170:171], v[130:131], v[168:169]
	v_pk_mul_f32 v[182:183], v[128:129], v[164:165]
	v_pk_mul_f32 v[164:165], v[116:117], v[164:165]
	v_mul_f32_e32 v183, v183, v183
	v_mul_f32_e32 v171, v171, v171
	v_fmac_f32_e32 v183, v182, v182
	v_fmac_f32_e32 v171, v170, v170
	v_mul_f32_e32 v165, v165, v165
	v_pk_mul_f32 v[168:169], v[118:119], v[168:169]
	v_add_f32_e32 v170, v183, v171
	v_fmac_f32_e32 v165, v164, v164
	v_add_f32_e32 v164, v165, v170
	v_mul_f32_e32 v165, v169, v169
	v_fmac_f32_e32 v165, v168, v168
	v_add_f32_e32 v164, v165, v164
	v_mov_b32_e32 v165, v164
	s_nop 1
	v_permlane16_swap_b32_e32 v165, v164
	s_waitcnt lgkmcnt(0)
	v_add_f32_e32 v164, v164, v165
	v_mov_b32_e32 v165, v164
	s_nop 1
	v_permlane32_swap_b32_e32 v165, v164
	s_and_saveexec_b64 s[44:45], s[40:41]
	s_cbranch_execz .LBB0_282
	s_waitcnt lgkmcnt(0)
	v_add_f32_e32 v164, v164, v165
	ds_write_b32 v209, v164 offset:16
.LBB0_282:
	s_or_b64 exec, exec, s[44:45]
	ds_read_b32 v164, v223 offset:128
	s_waitcnt lgkmcnt(0)
	v_pk_mul_f32 v[168:169], v[98:99], v[164:165] op_sel_hi:[1,0]
	v_pk_mul_f32 v[170:171], v[96:97], v[164:165] op_sel_hi:[1,0]
	v_pk_mul_f32 v[182:183], v[94:95], v[164:165] op_sel_hi:[1,0]
	v_pk_mul_f32 v[184:185], v[92:93], v[164:165] op_sel_hi:[1,0]
	v_mul_f32_e32 v165, v171, v171
	v_mul_f32_e32 v169, v169, v169
	v_fmac_f32_e32 v165, v170, v170
	v_fmac_f32_e32 v169, v168, v168
	v_mul_f32_e32 v168, v185, v185
	v_add_f32_e32 v165, v165, v169
	v_fmac_f32_e32 v168, v184, v184
	v_add_f32_e32 v165, v168, v165
	v_mul_f32_e32 v168, v183, v183
	v_fmac_f32_e32 v168, v182, v182
	v_add_f32_e32 v165, v168, v165
	v_mov_b32_e32 v168, v165
	s_nop 1
	v_permlane16_swap_b32_e32 v168, v165
	s_waitcnt lgkmcnt(0)
	v_add_f32_e32 v165, v165, v168
	v_mov_b32_e32 v168, v165
	s_nop 1
	v_permlane32_swap_b32_e32 v168, v165
	s_and_saveexec_b64 s[44:45], s[40:41]
	s_cbranch_execz .LBB0_284
	s_waitcnt lgkmcnt(0)
	v_add_f32_e32 v165, v165, v168
	ds_write_b32 v211, v165
.LBB0_284:
	s_or_b64 exec, exec, s[44:45]
	v_mov_b32_e32 v165, v164
	s_waitcnt lgkmcnt(0)
	v_mov_b32_e32 v168, v164
	v_mov_b32_e32 v169, v164
	v_pk_mul_f32 v[170:171], v[86:87], v[168:169]
	v_pk_mul_f32 v[182:183], v[84:85], v[164:165]
	v_pk_mul_f32 v[164:165], v[80:81], v[164:165]
	v_mul_f32_e32 v183, v183, v183
	v_mul_f32_e32 v171, v171, v171
	v_fmac_f32_e32 v183, v182, v182
	v_fmac_f32_e32 v171, v170, v170
	v_mul_f32_e32 v165, v165, v165
	v_pk_mul_f32 v[168:169], v[82:83], v[168:169]
	v_add_f32_e32 v170, v183, v171
	v_fmac_f32_e32 v165, v164, v164
	v_add_f32_e32 v164, v165, v170
	v_mul_f32_e32 v165, v169, v169
	v_fmac_f32_e32 v165, v168, v168
	v_add_f32_e32 v164, v165, v164
	v_mov_b32_e32 v165, v164
	s_nop 1
	v_permlane16_swap_b32_e32 v165, v164
	s_waitcnt lgkmcnt(0)
	v_add_f32_e32 v164, v164, v165
	v_mov_b32_e32 v165, v164
	s_nop 1
	v_permlane32_swap_b32_e32 v165, v164
	s_and_saveexec_b64 s[44:45], s[40:41]
	s_cbranch_execz .LBB0_286
	s_waitcnt lgkmcnt(0)
	v_add_f32_e32 v164, v164, v165
	ds_write_b32 v211, v164 offset:16
.LBB0_286:
	s_or_b64 exec, exec, s[44:45]
	ds_read_b32 v164, v223 offset:192
	s_waitcnt lgkmcnt(0)
	v_pk_mul_f32 v[168:169], v[78:79], v[164:165] op_sel_hi:[1,0]
	v_pk_mul_f32 v[170:171], v[76:77], v[164:165] op_sel_hi:[1,0]
	v_pk_mul_f32 v[182:183], v[74:75], v[164:165] op_sel_hi:[1,0]
	v_pk_mul_f32 v[184:185], v[72:73], v[164:165] op_sel_hi:[1,0]
	v_mul_f32_e32 v165, v171, v171
	v_mul_f32_e32 v169, v169, v169
	v_fmac_f32_e32 v165, v170, v170
	v_fmac_f32_e32 v169, v168, v168
	v_mul_f32_e32 v168, v185, v185
	v_add_f32_e32 v165, v165, v169
	v_fmac_f32_e32 v168, v184, v184
	v_add_f32_e32 v165, v168, v165
	v_mul_f32_e32 v168, v183, v183
	v_fmac_f32_e32 v168, v182, v182
	v_add_f32_e32 v165, v168, v165
	v_mov_b32_e32 v168, v165
	s_nop 1
	v_permlane16_swap_b32_e32 v168, v165
	s_waitcnt lgkmcnt(0)
	v_add_f32_e32 v165, v165, v168
	v_mov_b32_e32 v168, v165
	s_nop 1
	v_permlane32_swap_b32_e32 v168, v165
	s_and_saveexec_b64 s[44:45], s[40:41]
	s_cbranch_execz .LBB0_288
	s_waitcnt lgkmcnt(0)
	v_add_f32_e32 v165, v165, v168
	ds_write_b32 v213, v165
.LBB0_288:
	s_or_b64 exec, exec, s[44:45]
	v_mov_b32_e32 v165, v164
	s_waitcnt lgkmcnt(0)
	v_mov_b32_e32 v168, v164
	v_mov_b32_e32 v169, v164
	v_pk_mul_f32 v[170:171], v[70:71], v[168:169]
	v_pk_mul_f32 v[182:183], v[68:69], v[164:165]
	v_pk_mul_f32 v[164:165], v[64:65], v[164:165]
	v_mul_f32_e32 v183, v183, v183
	v_mul_f32_e32 v171, v171, v171
	v_fmac_f32_e32 v183, v182, v182
	v_fmac_f32_e32 v171, v170, v170
	v_mul_f32_e32 v165, v165, v165
	v_pk_mul_f32 v[168:169], v[66:67], v[168:169]
	v_add_f32_e32 v170, v183, v171
	v_fmac_f32_e32 v165, v164, v164
	v_add_f32_e32 v164, v165, v170
	v_mul_f32_e32 v165, v169, v169
	v_fmac_f32_e32 v165, v168, v168
	v_add_f32_e32 v164, v165, v164
	v_mov_b32_e32 v165, v164
	s_nop 1
	v_permlane16_swap_b32_e32 v165, v164
	s_waitcnt lgkmcnt(0)
	v_add_f32_e32 v164, v164, v165
	v_mov_b32_e32 v165, v164
	s_nop 1
	v_permlane32_swap_b32_e32 v165, v164
	s_and_saveexec_b64 s[44:45], s[40:41]
	s_cbranch_execz .LBB0_290
	s_waitcnt lgkmcnt(0)
	v_add_f32_e32 v164, v164, v165
	ds_write_b32 v213, v164 offset:16
.LBB0_290:
	s_or_b64 exec, exec, s[44:45]
	ds_read_b32 v164, v223 offset:512
	s_waitcnt lgkmcnt(0)
	v_pk_mul_f32 v[168:169], v[62:63], v[164:165] op_sel_hi:[1,0]
	v_pk_mul_f32 v[170:171], v[60:61], v[164:165] op_sel_hi:[1,0]
	v_pk_mul_f32 v[182:183], v[58:59], v[164:165] op_sel_hi:[1,0]
	v_pk_mul_f32 v[184:185], v[56:57], v[164:165] op_sel_hi:[1,0]
	v_mul_f32_e32 v165, v171, v171
	v_mul_f32_e32 v169, v169, v169
	v_fmac_f32_e32 v165, v170, v170
	v_fmac_f32_e32 v169, v168, v168
	v_mul_f32_e32 v168, v185, v185
	v_add_f32_e32 v165, v165, v169
	v_fmac_f32_e32 v168, v184, v184
	v_add_f32_e32 v165, v168, v165
	v_mul_f32_e32 v168, v183, v183
	v_fmac_f32_e32 v168, v182, v182
	v_add_f32_e32 v165, v168, v165
	v_mov_b32_e32 v168, v165
	s_nop 1
	v_permlane16_swap_b32_e32 v168, v165
	s_waitcnt lgkmcnt(0)
	v_add_f32_e32 v165, v165, v168
	v_mov_b32_e32 v168, v165
	s_nop 1
	v_permlane32_swap_b32_e32 v168, v165
	s_and_saveexec_b64 s[44:45], s[40:41]
	s_cbranch_execz .LBB0_292
	s_waitcnt lgkmcnt(0)
	v_add_f32_e32 v165, v165, v168
	ds_write_b32 v215, v165
.LBB0_292:
	s_or_b64 exec, exec, s[44:45]
	v_mov_b32_e32 v165, v164
	s_waitcnt lgkmcnt(0)
	v_mov_b32_e32 v168, v164
	v_mov_b32_e32 v169, v164
	v_pk_mul_f32 v[170:171], v[54:55], v[168:169]
	v_pk_mul_f32 v[182:183], v[52:53], v[164:165]
	v_pk_mul_f32 v[164:165], v[48:49], v[164:165]
	v_mul_f32_e32 v183, v183, v183
	v_mul_f32_e32 v171, v171, v171
	v_fmac_f32_e32 v183, v182, v182
	v_fmac_f32_e32 v171, v170, v170
	v_mul_f32_e32 v165, v165, v165
	v_pk_mul_f32 v[168:169], v[50:51], v[168:169]
	v_add_f32_e32 v170, v183, v171
	v_fmac_f32_e32 v165, v164, v164
	v_add_f32_e32 v164, v165, v170
	v_mul_f32_e32 v165, v169, v169
	v_fmac_f32_e32 v165, v168, v168
	v_add_f32_e32 v164, v165, v164
	v_mov_b32_e32 v165, v164
	s_nop 1
	v_permlane16_swap_b32_e32 v165, v164
	s_waitcnt lgkmcnt(0)
	v_add_f32_e32 v164, v164, v165
	v_mov_b32_e32 v165, v164
	s_nop 1
	v_permlane32_swap_b32_e32 v165, v164
	s_and_saveexec_b64 s[44:45], s[40:41]
	s_cbranch_execz .LBB0_294
	s_waitcnt lgkmcnt(0)
	v_add_f32_e32 v164, v164, v165
	ds_write_b32 v215, v164 offset:16
.LBB0_294:
	s_or_b64 exec, exec, s[44:45]
	ds_read_b32 v164, v223 offset:576
	s_waitcnt lgkmcnt(0)
	v_pk_mul_f32 v[168:169], v[46:47], v[164:165] op_sel_hi:[1,0]
	v_pk_mul_f32 v[170:171], v[44:45], v[164:165] op_sel_hi:[1,0]
	v_pk_mul_f32 v[182:183], v[42:43], v[164:165] op_sel_hi:[1,0]
	v_pk_mul_f32 v[184:185], v[40:41], v[164:165] op_sel_hi:[1,0]
	v_mul_f32_e32 v165, v171, v171
	v_mul_f32_e32 v169, v169, v169
	v_fmac_f32_e32 v165, v170, v170
	v_fmac_f32_e32 v169, v168, v168
	v_mul_f32_e32 v168, v185, v185
	v_add_f32_e32 v165, v165, v169
	v_fmac_f32_e32 v168, v184, v184
	v_add_f32_e32 v165, v168, v165
	v_mul_f32_e32 v168, v183, v183
	v_fmac_f32_e32 v168, v182, v182
	v_add_f32_e32 v165, v168, v165
	v_mov_b32_e32 v168, v165
	s_nop 1
	v_permlane16_swap_b32_e32 v168, v165
	s_waitcnt lgkmcnt(0)
	v_add_f32_e32 v165, v165, v168
	v_mov_b32_e32 v168, v165
	s_nop 1
	v_permlane32_swap_b32_e32 v168, v165
	s_and_saveexec_b64 s[44:45], s[40:41]
	s_cbranch_execz .LBB0_296
	s_waitcnt lgkmcnt(0)
	v_add_f32_e32 v165, v165, v168
	ds_write_b32 v217, v165
.LBB0_296:
	s_or_b64 exec, exec, s[44:45]
	v_mov_b32_e32 v165, v164
	s_waitcnt lgkmcnt(0)
	v_mov_b32_e32 v168, v164
	v_mov_b32_e32 v169, v164
	v_pk_mul_f32 v[170:171], v[38:39], v[168:169]
	v_pk_mul_f32 v[182:183], v[36:37], v[164:165]
	v_pk_mul_f32 v[164:165], v[32:33], v[164:165]
	v_mul_f32_e32 v183, v183, v183
	v_mul_f32_e32 v171, v171, v171
	v_fmac_f32_e32 v183, v182, v182
	v_fmac_f32_e32 v171, v170, v170
	v_mul_f32_e32 v165, v165, v165
	v_pk_mul_f32 v[168:169], v[34:35], v[168:169]
	v_add_f32_e32 v170, v183, v171
	v_fmac_f32_e32 v165, v164, v164
	v_add_f32_e32 v164, v165, v170
	v_mul_f32_e32 v165, v169, v169
	v_fmac_f32_e32 v165, v168, v168
	v_add_f32_e32 v164, v165, v164
	v_mov_b32_e32 v165, v164
	s_nop 1
	v_permlane16_swap_b32_e32 v165, v164
	s_waitcnt lgkmcnt(0)
	v_add_f32_e32 v164, v164, v165
	v_mov_b32_e32 v165, v164
	s_nop 1
	v_permlane32_swap_b32_e32 v165, v164
	s_and_saveexec_b64 s[44:45], s[40:41]
	s_cbranch_execz .LBB0_298
	s_waitcnt lgkmcnt(0)
	v_add_f32_e32 v164, v164, v165
	ds_write_b32 v217, v164 offset:16
.LBB0_298:
	s_or_b64 exec, exec, s[44:45]
	ds_read_b32 v164, v223 offset:640
	s_waitcnt lgkmcnt(0)
	v_pk_mul_f32 v[168:169], v[30:31], v[164:165] op_sel_hi:[1,0]
	v_pk_mul_f32 v[170:171], v[28:29], v[164:165] op_sel_hi:[1,0]
	v_pk_mul_f32 v[182:183], v[26:27], v[164:165] op_sel_hi:[1,0]
	v_pk_mul_f32 v[184:185], v[24:25], v[164:165] op_sel_hi:[1,0]
	v_mul_f32_e32 v165, v171, v171
	v_mul_f32_e32 v169, v169, v169
	v_fmac_f32_e32 v165, v170, v170
	v_fmac_f32_e32 v169, v168, v168
	v_mul_f32_e32 v168, v185, v185
	v_add_f32_e32 v165, v165, v169
	v_fmac_f32_e32 v168, v184, v184
	v_add_f32_e32 v165, v168, v165
	v_mul_f32_e32 v168, v183, v183
	v_fmac_f32_e32 v168, v182, v182
	v_add_f32_e32 v165, v168, v165
	v_mov_b32_e32 v168, v165
	s_nop 1
	v_permlane16_swap_b32_e32 v168, v165
	s_waitcnt lgkmcnt(0)
	v_add_f32_e32 v165, v165, v168
	v_mov_b32_e32 v168, v165
	s_nop 1
	v_permlane32_swap_b32_e32 v168, v165
	s_and_saveexec_b64 s[44:45], s[40:41]
	s_cbranch_execz .LBB0_300
	s_waitcnt lgkmcnt(0)
	v_add_f32_e32 v165, v165, v168
	ds_write_b32 v219, v165
.LBB0_300:
	s_or_b64 exec, exec, s[44:45]
	v_mov_b32_e32 v165, v164
	s_waitcnt lgkmcnt(0)
	v_mov_b32_e32 v168, v164
	v_mov_b32_e32 v169, v164
	v_pk_mul_f32 v[170:171], v[22:23], v[168:169]
	v_pk_mul_f32 v[182:183], v[20:21], v[164:165]
	v_pk_mul_f32 v[164:165], v[16:17], v[164:165]
	v_mul_f32_e32 v183, v183, v183
	v_mul_f32_e32 v171, v171, v171
	v_fmac_f32_e32 v183, v182, v182
	v_fmac_f32_e32 v171, v170, v170
	v_mul_f32_e32 v165, v165, v165
	v_pk_mul_f32 v[168:169], v[18:19], v[168:169]
	v_add_f32_e32 v170, v183, v171
	v_fmac_f32_e32 v165, v164, v164
	v_add_f32_e32 v164, v165, v170
	v_mul_f32_e32 v165, v169, v169
	v_fmac_f32_e32 v165, v168, v168
	v_add_f32_e32 v164, v165, v164
	v_mov_b32_e32 v165, v164
	s_nop 1
	v_permlane16_swap_b32_e32 v165, v164
	s_waitcnt lgkmcnt(0)
	v_add_f32_e32 v164, v164, v165
	v_mov_b32_e32 v165, v164
	s_nop 1
	v_permlane32_swap_b32_e32 v165, v164
	s_and_saveexec_b64 s[44:45], s[40:41]
	s_cbranch_execz .LBB0_302
	s_waitcnt lgkmcnt(0)
	v_add_f32_e32 v164, v164, v165
	ds_write_b32 v219, v164 offset:16
.LBB0_302:
	s_or_b64 exec, exec, s[44:45]
	ds_read_b32 v164, v223 offset:704
	s_waitcnt lgkmcnt(0)
	v_pk_mul_f32 v[168:169], v[14:15], v[164:165] op_sel_hi:[1,0]
	v_pk_mul_f32 v[170:171], v[12:13], v[164:165] op_sel_hi:[1,0]
	v_pk_mul_f32 v[182:183], v[10:11], v[164:165] op_sel_hi:[1,0]
	v_pk_mul_f32 v[184:185], v[8:9], v[164:165] op_sel_hi:[1,0]
	v_mul_f32_e32 v165, v171, v171
	v_mul_f32_e32 v169, v169, v169
	v_fmac_f32_e32 v165, v170, v170
	v_fmac_f32_e32 v169, v168, v168
	v_mul_f32_e32 v168, v185, v185
	v_add_f32_e32 v165, v165, v169
	v_fmac_f32_e32 v168, v184, v184
	v_add_f32_e32 v165, v168, v165
	v_mul_f32_e32 v168, v183, v183
	v_fmac_f32_e32 v168, v182, v182
	v_add_f32_e32 v165, v168, v165
	v_mov_b32_e32 v168, v165
	s_nop 1
	v_permlane16_swap_b32_e32 v168, v165
	s_waitcnt lgkmcnt(0)
	v_add_f32_e32 v165, v165, v168
	v_mov_b32_e32 v168, v165
	s_nop 1
	v_permlane32_swap_b32_e32 v168, v165
	s_and_saveexec_b64 s[44:45], s[40:41]
	s_cbranch_execz .LBB0_304
	s_waitcnt lgkmcnt(0)
	v_add_f32_e32 v165, v165, v168
	ds_write_b32 v221, v165
.LBB0_304:
	s_or_b64 exec, exec, s[44:45]
	v_mov_b32_e32 v165, v164
	s_waitcnt lgkmcnt(0)
	v_mov_b32_e32 v168, v164
	v_mov_b32_e32 v169, v164
	v_pk_mul_f32 v[170:171], v[6:7], v[168:169]
	v_pk_mul_f32 v[182:183], v[4:5], v[164:165]
	v_pk_mul_f32 v[164:165], v[0:1], v[164:165]
	v_mul_f32_e32 v183, v183, v183
	v_mul_f32_e32 v171, v171, v171
	v_fmac_f32_e32 v183, v182, v182
	v_fmac_f32_e32 v171, v170, v170
	v_mul_f32_e32 v165, v165, v165
	v_pk_mul_f32 v[168:169], v[2:3], v[168:169]
	v_add_f32_e32 v170, v183, v171
	v_fmac_f32_e32 v165, v164, v164
	v_add_f32_e32 v164, v165, v170
	v_mul_f32_e32 v165, v169, v169
	v_fmac_f32_e32 v165, v168, v168
	v_add_f32_e32 v164, v165, v164
	v_mov_b32_e32 v165, v164
	s_nop 1
	v_permlane16_swap_b32_e32 v165, v164
	s_waitcnt lgkmcnt(0)
	v_add_f32_e32 v164, v164, v165
	v_mov_b32_e32 v165, v164
	s_nop 1
	v_permlane32_swap_b32_e32 v165, v164
	s_and_saveexec_b64 s[44:45], s[40:41]
	s_cbranch_execz .LBB0_306
	s_waitcnt lgkmcnt(0)
	v_add_f32_e32 v164, v164, v165
	ds_write_b32 v221, v164 offset:16

.LBB0_727:
	s_add_u32 s42, s46, 0x100
	s_addc_u32 s43, s47, 0
	s_add_i32 s6, 0, 0x10000
	s_cmp_eq_u32 s77, 28
	s_cselect_b32 s51, s29, s43
	s_cselect_b32 s50, s28, s42
	s_cselect_b32 s49, s30, s76
	s_cselect_b32 s48, s74, s75
	s_add_i32 s7, 0, 0x14000
	v_add_u32_e32 v132, s6, v220
	v_add_u32_e32 v160, s7, v220
	ds_read_b128 v[112:115], v132
	ds_read_b128 v[116:119], v132 offset:1024
	ds_read_b128 v[128:131], v132 offset:2048
	ds_read_b128 v[132:135], v132 offset:3072
	ds_read_b128 v[140:143], v160
	ds_read_b128 v[144:147], v160 offset:1024
	ds_read_b128 v[156:159], v160 offset:2048
	ds_read_b128 v[160:163], v160 offset:3072
	v_lshl_add_u64 v[198:199], s[46:47], 0, v[184:185]
	s_add_i32 m0, s52, 0xc000
	ds_read_b128 v[164:167], v222
	ds_read_b128 v[168:171], v222 offset:1024
	ds_read_b128 v[172:175], v222 offset:2048
	ds_read_b128 v[176:179], v222 offset:3072
	ds_read_b128 v[188:191], v222 offset:4096
	ds_read_b128 v[206:209], v222 offset:5120
	ds_read_b128 v[210:213], v222 offset:6144
	ds_read_b128 v[214:217], v222 offset:7168
	global_load_lds_dwordx4 v[198:199], off
	v_lshl_add_u64 v[198:199], s[46:47], 0, v[186:187]
	s_add_i32 m0, s52, 0xe000
	s_nop 0
	global_load_lds_dwordx4 v[198:199], off
	s_add_i32 vcc_lo, s77, 2
	s_lshl_b32 vcc_lo, vcc_lo, 16
	s_lshl_b32 vcc_hi, s13, 21
	s_add_i32 vcc_lo, vcc_lo, vcc_hi
	s_lshl_b32 vcc_hi, s25, 4
	s_add_i32 vcc_lo, vcc_lo, vcc_hi
	s_lshl_b32 vcc_hi, s12, 10
	s_add_i32 vcc_lo, vcc_lo, vcc_hi
	s_add_u32 vcc_lo, s22, vcc_lo
	s_addc_u32 vcc_hi, s23, 0
	s_mov_b32 m0, 0x22c00
	s_nop 0
	global_load_lds_dwordx4 v224, vcc
	s_waitcnt vmcnt(9)
	s_waitcnt lgkmcnt(0)
	s_barrier
	s_setprio 1
	s_waitcnt lgkmcnt(0)
	v_mfma_f32_16x16x32_bf16 v[152:155], v[112:115], v[164:167], v[152:155]
	v_mfma_f32_16x16x32_bf16 v[148:151], v[128:131], v[164:167], v[148:151]
	v_mfma_f32_16x16x32_bf16 v[108:111], v[112:115], v[172:175], v[108:111]
	v_mfma_f32_16x16x32_bf16 v[104:107], v[128:131], v[172:175], v[104:107]
	v_mfma_f32_16x16x32_bf16 v[92:95], v[112:115], v[188:191], v[92:95]
	v_mfma_f32_16x16x32_bf16 v[88:91], v[128:131], v[188:191], v[88:91]
	v_mfma_f32_16x16x32_bf16 v[76:79], v[112:115], v[210:213], v[76:79]
	v_mfma_f32_16x16x32_bf16 v[72:75], v[128:131], v[210:213], v[72:75]
	v_mfma_f32_16x16x32_bf16 v[152:155], v[116:119], v[168:171], v[152:155]
	v_mfma_f32_16x16x32_bf16 v[148:151], v[132:135], v[168:171], v[148:151]
	v_mfma_f32_16x16x32_bf16 v[108:111], v[116:119], v[176:179], v[108:111]
	v_mfma_f32_16x16x32_bf16 v[104:107], v[132:135], v[176:179], v[104:107]
	v_mfma_f32_16x16x32_bf16 v[92:95], v[116:119], v[206:209], v[92:95]
	v_mfma_f32_16x16x32_bf16 v[88:91], v[132:135], v[206:209], v[88:91]
	v_mfma_f32_16x16x32_bf16 v[76:79], v[116:119], v[214:217], v[76:79]
	v_mfma_f32_16x16x32_bf16 v[72:75], v[132:135], v[214:217], v[72:75]
	s_setprio 0
	s_setprio 1
	v_mfma_f32_16x16x32_bf16 v[124:127], v[140:143], v[164:167], v[124:127]
	v_mfma_f32_16x16x32_bf16 v[120:123], v[156:159], v[164:167], v[120:123]
	v_mfma_f32_16x16x32_bf16 v[100:103], v[140:143], v[172:175], v[100:103]
	v_mfma_f32_16x16x32_bf16 v[96:99], v[156:159], v[172:175], v[96:99]
	v_mfma_f32_16x16x32_bf16 v[84:87], v[140:143], v[188:191], v[84:87]
	v_mfma_f32_16x16x32_bf16 v[80:83], v[156:159], v[188:191], v[80:83]
	v_mfma_f32_16x16x32_bf16 v[68:71], v[140:143], v[210:213], v[68:71]
	v_mfma_f32_16x16x32_bf16 v[64:67], v[156:159], v[210:213], v[64:67]
	v_mfma_f32_16x16x32_bf16 v[124:127], v[144:147], v[168:171], v[124:127]
	v_mfma_f32_16x16x32_bf16 v[120:123], v[160:163], v[168:171], v[120:123]
	v_mfma_f32_16x16x32_bf16 v[100:103], v[144:147], v[176:179], v[100:103]
	v_mfma_f32_16x16x32_bf16 v[96:99], v[160:163], v[176:179], v[96:99]
	v_mfma_f32_16x16x32_bf16 v[84:87], v[144:147], v[206:209], v[84:87]
	v_mfma_f32_16x16x32_bf16 v[80:83], v[160:163], v[206:209], v[80:83]
	v_mfma_f32_16x16x32_bf16 v[68:71], v[144:147], v[214:217], v[68:71]
	v_mfma_f32_16x16x32_bf16 v[64:67], v[160:163], v[214:217], v[64:67]
	s_setprio 0
	s_barrier
	s_add_i32 s6, s6, s25
	v_lshl_add_u64 v[198:199], s[48:49], 0, v[138:139]
	s_mov_b32 m0, s6
	ds_read_b128 v[164:167], v222 offset:16384
	ds_read_b128 v[168:171], v222 offset:17408
	ds_read_b128 v[172:175], v222 offset:18432
	ds_read_b128 v[176:179], v222 offset:19456
	ds_read_b128 v[188:191], v222 offset:20480
	ds_read_b128 v[206:209], v222 offset:21504
	ds_read_b128 v[210:213], v222 offset:22528
	ds_read_b128 v[214:217], v222 offset:23552
	global_load_lds_dwordx4 v[198:199], off
	s_add_i32 m0, s6, 0x2000
	s_add_u32 s46, s48, 0x2000
	v_lshl_add_u64 v[198:199], s[48:49], 0, v[136:137]
	s_addc_u32 s47, s49, 0
	s_add_i32 s6, s7, s25
	global_load_lds_dwordx4 v[198:199], off
	v_lshl_add_u64 v[198:199], s[46:47], 0, v[138:139]
	s_mov_b32 m0, s6
	v_lshl_add_u64 v[200:201], s[50:51], 0, v[180:181]
	global_load_lds_dwordx4 v[198:199], off
	v_lshl_add_u64 v[198:199], s[46:47], 0, v[136:137]
	s_add_i32 m0, s6, 0x2000
	s_nop 0
	global_load_lds_dwordx4 v[198:199], off
	v_lshl_add_u64 v[198:199], s[50:51], 0, v[182:183]
	s_mov_b32 m0, s52
	s_nop 0
	global_load_lds_dwordx4 v[198:199], off
	s_mov_b32 m0, s53
	s_nop 0
	global_load_lds_dwordx4 v[200:201], off
	s_waitcnt vmcnt(9)
	s_waitcnt lgkmcnt(0)
	s_barrier
	s_setprio 1
	s_waitcnt lgkmcnt(0)
	v_mfma_f32_16x16x32_bf16 v[60:63], v[112:115], v[164:167], v[60:63]
	v_mfma_f32_16x16x32_bf16 v[56:59], v[128:131], v[164:167], v[56:59]
	v_mfma_f32_16x16x32_bf16 v[44:47], v[112:115], v[172:175], v[44:47]
	v_mfma_f32_16x16x32_bf16 v[40:43], v[128:131], v[172:175], v[40:43]
	v_mfma_f32_16x16x32_bf16 v[28:31], v[112:115], v[188:191], v[28:31]
	v_mfma_f32_16x16x32_bf16 v[24:27], v[128:131], v[188:191], v[24:27]
	v_mfma_f32_16x16x32_bf16 v[12:15], v[112:115], v[210:213], v[12:15]
	v_mfma_f32_16x16x32_bf16 v[8:11], v[128:131], v[210:213], v[8:11]
	v_mfma_f32_16x16x32_bf16 v[60:63], v[116:119], v[168:171], v[60:63]
	v_mfma_f32_16x16x32_bf16 v[56:59], v[132:135], v[168:171], v[56:59]
	v_mfma_f32_16x16x32_bf16 v[44:47], v[116:119], v[176:179], v[44:47]
	v_mfma_f32_16x16x32_bf16 v[40:43], v[132:135], v[176:179], v[40:43]
	v_mfma_f32_16x16x32_bf16 v[28:31], v[116:119], v[206:209], v[28:31]
	v_mfma_f32_16x16x32_bf16 v[24:27], v[132:135], v[206:209], v[24:27]
	v_mfma_f32_16x16x32_bf16 v[12:15], v[116:119], v[214:217], v[12:15]
	v_mfma_f32_16x16x32_bf16 v[8:11], v[132:135], v[214:217], v[8:11]
	s_setprio 0
	s_setprio 1
	v_mfma_f32_16x16x32_bf16 v[52:55], v[140:143], v[164:167], v[52:55]
	v_mfma_f32_16x16x32_bf16 v[48:51], v[156:159], v[164:167], v[48:51]
	v_mfma_f32_16x16x32_bf16 v[36:39], v[140:143], v[172:175], v[36:39]
	v_mfma_f32_16x16x32_bf16 v[32:35], v[156:159], v[172:175], v[32:35]
	v_mfma_f32_16x16x32_bf16 v[20:23], v[140:143], v[188:191], v[20:23]
	v_mfma_f32_16x16x32_bf16 v[16:19], v[156:159], v[188:191], v[16:19]
	v_mfma_f32_16x16x32_bf16 v[4:7], v[140:143], v[210:213], v[4:7]
	v_mfma_f32_16x16x32_bf16 v[0:3], v[156:159], v[210:213], v[0:3]
	v_mfma_f32_16x16x32_bf16 v[52:55], v[144:147], v[168:171], v[52:55]
	v_mfma_f32_16x16x32_bf16 v[48:51], v[160:163], v[168:171], v[48:51]
	v_mfma_f32_16x16x32_bf16 v[36:39], v[144:147], v[176:179], v[36:39]
	v_mfma_f32_16x16x32_bf16 v[32:35], v[160:163], v[176:179], v[32:35]
	v_mfma_f32_16x16x32_bf16 v[20:23], v[144:147], v[206:209], v[20:23]
	v_mfma_f32_16x16x32_bf16 v[16:19], v[160:163], v[206:209], v[16:19]
	v_mfma_f32_16x16x32_bf16 v[4:7], v[144:147], v[214:217], v[4:7]
	v_mfma_f32_16x16x32_bf16 v[0:3], v[160:163], v[214:217], v[0:3]
	s_setprio 0
	s_barrier
	s_add_i32 s6, 0, 0x18000
	s_add_i32 s7, 0, 0x1c000
	v_add_u32_e32 v132, s6, v220
	v_add_u32_e32 v160, s7, v220
	ds_read_b128 v[112:115], v132
	ds_read_b128 v[116:119], v132 offset:1024
	ds_read_b128 v[128:131], v132 offset:2048
	ds_read_b128 v[132:135], v132 offset:3072
	ds_read_b128 v[140:143], v160
	ds_read_b128 v[144:147], v160 offset:1024
	ds_read_b128 v[156:159], v160 offset:2048
	ds_read_b128 v[160:163], v160 offset:3072
	s_add_u32 s46, s50, 0x84000
	s_addc_u32 s47, s51, 0
	s_mov_b32 m0, s54
	v_lshl_add_u64 v[218:219], s[46:47], 0, v[182:183]
	ds_read_b128 v[164:167], v222 offset:32768
	ds_read_b128 v[168:171], v222 offset:33792
	ds_read_b128 v[172:175], v222 offset:34816
	ds_read_b128 v[176:179], v222 offset:35840
	ds_read_b128 v[188:191], v222 offset:36864
	ds_read_b128 v[206:209], v222 offset:37888
	ds_read_b128 v[210:213], v222 offset:38912
	ds_read_b128 v[214:217], v222 offset:39936
	global_load_lds_dwordx4 v[218:219], off
	v_lshl_add_u64 v[218:219], s[46:47], 0, v[180:181]
	s_mov_b32 m0, s55
	s_nop 0
	global_load_lds_dwordx4 v[218:219], off
	s_add_u32 vcc_lo, vcc_lo, 0x2000
	s_addc_u32 vcc_hi, vcc_hi, 0
	s_mov_b32 m0, 0x22c00
	s_nop 0
	global_load_lds_dwordx4 v224, vcc
	s_waitcnt vmcnt(9)
	s_waitcnt lgkmcnt(0)
	s_barrier
	s_setprio 1
	s_waitcnt lgkmcnt(0)
	v_mfma_f32_16x16x32_bf16 v[152:155], v[112:115], v[164:167], v[152:155]
	v_mfma_f32_16x16x32_bf16 v[148:151], v[128:131], v[164:167], v[148:151]
	v_mfma_f32_16x16x32_bf16 v[108:111], v[112:115], v[172:175], v[108:111]
	v_mfma_f32_16x16x32_bf16 v[104:107], v[128:131], v[172:175], v[104:107]
	v_mfma_f32_16x16x32_bf16 v[92:95], v[112:115], v[188:191], v[92:95]
	v_mfma_f32_16x16x32_bf16 v[88:91], v[128:131], v[188:191], v[88:91]
	v_mfma_f32_16x16x32_bf16 v[76:79], v[112:115], v[210:213], v[76:79]
	v_mfma_f32_16x16x32_bf16 v[72:75], v[128:131], v[210:213], v[72:75]
	v_mfma_f32_16x16x32_bf16 v[152:155], v[116:119], v[168:171], v[152:155]
	v_mfma_f32_16x16x32_bf16 v[148:151], v[132:135], v[168:171], v[148:151]
	v_mfma_f32_16x16x32_bf16 v[108:111], v[116:119], v[176:179], v[108:111]
	v_mfma_f32_16x16x32_bf16 v[104:107], v[132:135], v[176:179], v[104:107]
	v_mfma_f32_16x16x32_bf16 v[92:95], v[116:119], v[206:209], v[92:95]
	v_mfma_f32_16x16x32_bf16 v[88:91], v[132:135], v[206:209], v[88:91]
	v_mfma_f32_16x16x32_bf16 v[76:79], v[116:119], v[214:217], v[76:79]
	v_mfma_f32_16x16x32_bf16 v[72:75], v[132:135], v[214:217], v[72:75]
	s_setprio 0
	s_setprio 1
	v_mfma_f32_16x16x32_bf16 v[124:127], v[140:143], v[164:167], v[124:127]
	v_mfma_f32_16x16x32_bf16 v[120:123], v[156:159], v[164:167], v[120:123]
	v_mfma_f32_16x16x32_bf16 v[100:103], v[140:143], v[172:175], v[100:103]
	v_mfma_f32_16x16x32_bf16 v[96:99], v[156:159], v[172:175], v[96:99]
	v_mfma_f32_16x16x32_bf16 v[84:87], v[140:143], v[188:191], v[84:87]
	v_mfma_f32_16x16x32_bf16 v[80:83], v[156:159], v[188:191], v[80:83]
	v_mfma_f32_16x16x32_bf16 v[68:71], v[140:143], v[210:213], v[68:71]
	v_mfma_f32_16x16x32_bf16 v[64:67], v[156:159], v[210:213], v[64:67]
	v_mfma_f32_16x16x32_bf16 v[124:127], v[144:147], v[168:171], v[124:127]
	v_mfma_f32_16x16x32_bf16 v[120:123], v[160:163], v[168:171], v[120:123]
	v_mfma_f32_16x16x32_bf16 v[100:103], v[144:147], v[176:179], v[100:103]
	v_mfma_f32_16x16x32_bf16 v[96:99], v[160:163], v[176:179], v[96:99]
	v_mfma_f32_16x16x32_bf16 v[84:87], v[144:147], v[206:209], v[84:87]
	v_mfma_f32_16x16x32_bf16 v[80:83], v[160:163], v[206:209], v[80:83]
	v_mfma_f32_16x16x32_bf16 v[68:71], v[144:147], v[214:217], v[68:71]
	v_mfma_f32_16x16x32_bf16 v[64:67], v[160:163], v[214:217], v[64:67]
	s_setprio 0
	s_barrier
	s_add_u32 s46, s48, 0x40000
	s_addc_u32 s47, s49, 0
	s_add_i32 s6, s6, s25
	v_lshl_add_u64 v[218:219], s[46:47], 0, v[138:139]
	s_mov_b32 m0, s6
	ds_read_b128 v[164:167], v222 offset:49152
	ds_read_b128 v[168:171], v222 offset:50176
	ds_read_b128 v[172:175], v222 offset:51200
	ds_read_b128 v[176:179], v222 offset:52224
	ds_read_b128 v[188:191], v222 offset:53248
	ds_read_b128 v[206:209], v222 offset:54272
	ds_read_b128 v[210:213], v222 offset:55296
	ds_read_b128 v[214:217], v222 offset:56320
	global_load_lds_dwordx4 v[218:219], off
	s_add_i32 m0, s6, 0x2000
	v_lshl_add_u64 v[218:219], s[46:47], 0, v[136:137]
	s_add_u32 s46, s48, 0x42000
	s_addc_u32 s47, s49, 0
	s_add_i32 s6, s7, s25
	global_load_lds_dwordx4 v[218:219], off
	v_lshl_add_u64 v[218:219], s[46:47], 0, v[138:139]
	s_mov_b32 m0, s6
	v_lshl_add_u64 v[198:199], v[198:199], 0, s[36:37]
	global_load_lds_dwordx4 v[218:219], off
	v_lshl_add_u64 v[218:219], s[46:47], 0, v[136:137]
	s_add_i32 m0, s6, 0x2000
	s_nop 0
	global_load_lds_dwordx4 v[218:219], off
	s_mov_b32 m0, s58
	s_nop 0
	global_load_lds_dwordx4 v[198:199], off
	v_lshl_add_u64 v[198:199], v[200:201], 0, s[36:37]
	s_mov_b32 m0, s59
	s_nop 0
	global_load_lds_dwordx4 v[198:199], off
	s_waitcnt vmcnt(9)
	s_waitcnt lgkmcnt(0)
	s_barrier
	s_setprio 1
	s_waitcnt lgkmcnt(0)
	v_mfma_f32_16x16x32_bf16 v[60:63], v[112:115], v[164:167], v[60:63]
	v_mfma_f32_16x16x32_bf16 v[56:59], v[128:131], v[164:167], v[56:59]
	v_mfma_f32_16x16x32_bf16 v[44:47], v[112:115], v[172:175], v[44:47]
	v_mfma_f32_16x16x32_bf16 v[40:43], v[128:131], v[172:175], v[40:43]
	v_mfma_f32_16x16x32_bf16 v[28:31], v[112:115], v[188:191], v[28:31]
	v_mfma_f32_16x16x32_bf16 v[24:27], v[128:131], v[188:191], v[24:27]
	v_mfma_f32_16x16x32_bf16 v[12:15], v[112:115], v[210:213], v[12:15]
	v_mfma_f32_16x16x32_bf16 v[8:11], v[128:131], v[210:213], v[8:11]
	v_mfma_f32_16x16x32_bf16 v[60:63], v[116:119], v[168:171], v[60:63]
	v_mfma_f32_16x16x32_bf16 v[56:59], v[132:135], v[168:171], v[56:59]
	v_mfma_f32_16x16x32_bf16 v[44:47], v[116:119], v[176:179], v[44:47]
	v_mfma_f32_16x16x32_bf16 v[40:43], v[132:135], v[176:179], v[40:43]
	v_mfma_f32_16x16x32_bf16 v[28:31], v[116:119], v[206:209], v[28:31]
	v_mfma_f32_16x16x32_bf16 v[24:27], v[132:135], v[206:209], v[24:27]
	v_mfma_f32_16x16x32_bf16 v[12:15], v[116:119], v[214:217], v[12:15]
	v_mfma_f32_16x16x32_bf16 v[8:11], v[132:135], v[214:217], v[8:11]
	s_setprio 0
	s_setprio 1
	v_mfma_f32_16x16x32_bf16 v[52:55], v[140:143], v[164:167], v[52:55]
	v_mfma_f32_16x16x32_bf16 v[48:51], v[156:159], v[164:167], v[48:51]
	v_mfma_f32_16x16x32_bf16 v[36:39], v[140:143], v[172:175], v[36:39]
	v_mfma_f32_16x16x32_bf16 v[32:35], v[156:159], v[172:175], v[32:35]
	v_mfma_f32_16x16x32_bf16 v[20:23], v[140:143], v[188:191], v[20:23]
	v_mfma_f32_16x16x32_bf16 v[16:19], v[156:159], v[188:191], v[16:19]
	v_mfma_f32_16x16x32_bf16 v[4:7], v[140:143], v[210:213], v[4:7]
	v_mfma_f32_16x16x32_bf16 v[0:3], v[156:159], v[210:213], v[0:3]
	v_mfma_f32_16x16x32_bf16 v[52:55], v[144:147], v[168:171], v[52:55]
	v_mfma_f32_16x16x32_bf16 v[48:51], v[160:163], v[168:171], v[48:51]
	v_mfma_f32_16x16x32_bf16 v[36:39], v[144:147], v[176:179], v[36:39]
	v_mfma_f32_16x16x32_bf16 v[32:35], v[160:163], v[176:179], v[32:35]
	v_mfma_f32_16x16x32_bf16 v[20:23], v[144:147], v[206:209], v[20:23]
	v_mfma_f32_16x16x32_bf16 v[16:19], v[160:163], v[206:209], v[16:19]
	v_mfma_f32_16x16x32_bf16 v[4:7], v[144:147], v[214:217], v[4:7]
	v_mfma_f32_16x16x32_bf16 v[0:3], v[160:163], v[214:217], v[0:3]
	s_setprio 0
	s_barrier
	s_add_i32 s77, s77, 2
	s_add_u32 s75, s75, 0x80000
	s_addc_u32 s76, s76, 0
	s_cmp_gt_u32 s77, 29
	s_mov_b64 s[46:47], s[42:43]
	s_cbranch_scc0 .LBB0_727
	v_lshl_or_b32 v188, s12, 8, v221
	v_lshl_add_u32 v190, s13, 8, v197
	v_ashrrev_i32_e32 v189, 31, v188
	v_lshlrev_b64 v[198:199], 2, v[188:189]
	v_ashrrev_i32_e32 v191, 31, v190
	v_lshl_add_u64 v[206:207], s[22:23], 0, v[198:199]
	v_lshlrev_b64 v[200:201], 13, v[190:191]
	v_lshl_add_u64 v[112:113], v[206:207], 0, v[200:201]
	global_load_dwordx4 v[224:227], v[112:113], off offset:16
	global_load_dwordx4 v[228:231], v[112:113], off
	global_load_dwordx4 v[232:235], v[112:113], off offset:528
	global_load_dwordx4 v[244:247], v[112:113], off offset:512
	v_or_b32_e32 v214, 16, v190
	v_ashrrev_i32_e32 v215, 31, v214
	v_or_b32_e32 v210, 32, v190
	v_or_b32_e32 v208, 48, v190
	v_lshlrev_b64 v[218:219], 13, v[214:215]
	v_ashrrev_i32_e32 v211, 31, v210
	v_ashrrev_i32_e32 v209, 31, v208
	v_lshl_add_u64 v[112:113], v[206:207], 0, v[218:219]
	v_lshlrev_b64 v[216:217], 13, v[210:211]
	v_lshlrev_b64 v[212:213], 13, v[208:209]
	global_load_dwordx4 v[172:175], v[112:113], off offset:16
	global_load_dwordx4 v[176:179], v[112:113], off
	global_load_dwordx4 v[164:167], v[112:113], off offset:528
	global_load_dwordx4 v[168:171], v[112:113], off offset:512
	v_lshl_add_u64 v[112:113], v[206:207], 0, v[216:217]
	v_lshl_add_u64 v[116:117], v[206:207], 0, v[212:213]
	global_load_dwordx4 v[156:159], v[112:113], off offset:16
	global_load_dwordx4 v[160:163], v[112:113], off
	global_load_dwordx4 v[128:131], v[112:113], off offset:528
	global_load_dwordx4 v[144:147], v[112:113], off offset:512
	global_load_dwordx4 v[132:135], v[116:117], off offset:16
	global_load_dwordx4 v[140:143], v[116:117], off
	s_nop 0
	global_load_dwordx4 v[112:115], v[116:117], off offset:528
	s_nop 0
	global_load_dwordx4 v[116:119], v[116:117], off offset:512
	v_lshl_add_u64 v[200:201], s[82:83], 0, v[200:201]
	v_lshl_add_u64 v[198:199], v[200:201], 0, v[198:199]
	v_mov_b64_e32 v[200:201], s[4:5]
	s_lshl_b32 s42, s12, 2
	v_mad_i64_i32 v[200:201], s[12:13], v190, s66, v[200:201]
	v_lshl_add_u64 v[200:201], v[188:189], 1, v[200:201]
	s_ashr_i32 s43, s42, 31
	s_waitcnt vmcnt(12)
	v_pk_add_f32 v[148:149], v[148:149], v[224:225]
	v_pk_add_f32 v[154:155], v[154:155], v[230:231]
	v_pk_add_f32 v[152:153], v[152:153], v[228:229]
	v_mul_f32_e32 v224, v155, v155
	v_mul_f32_e32 v223, v153, v153
	v_fmac_f32_e32 v223, v152, v152
	v_fmac_f32_e32 v224, v154, v154
	v_add_f32_e32 v223, v223, v224
	v_mul_f32_e32 v224, v149, v149
	v_pk_add_f32 v[126:127], v[126:127], v[246:247]
	v_pk_add_f32 v[124:125], v[124:125], v[244:245]
	v_pk_add_f32 v[150:151], v[150:151], v[226:227]
	global_store_dwordx4 v[198:199], v[152:155], off
	global_store_dwordx4 v[198:199], v[148:151], off offset:16
	v_fmac_f32_e32 v224, v148, v148
	v_cvt_pk_bf16_f32 v152, v152, v153
	v_cvt_pk_bf16_f32 v153, v154, v155
	v_cvt_pk_bf16_f32 v154, v148, v149
	v_pk_add_f32 v[120:121], v[120:121], v[232:233]
	v_mul_f32_e32 v148, v125, v125
	v_mul_f32_e32 v149, v127, v127
	v_fmac_f32_e32 v148, v124, v124
	v_fmac_f32_e32 v149, v126, v126
	v_add_f32_e32 v148, v148, v149
	v_mul_f32_e32 v149, v121, v121
	v_cvt_pk_bf16_f32 v155, v150, v151
	global_store_dwordx4 v[200:201], v[152:155], off
	v_pk_add_f32 v[122:123], v[122:123], v[234:235]
	global_store_dwordx4 v[198:199], v[124:127], off offset:512
	global_store_dwordx4 v[198:199], v[120:123], off offset:528
	v_fmac_f32_e32 v149, v120, v120
	v_cvt_pk_bf16_f32 v124, v124, v125
	v_cvt_pk_bf16_f32 v125, v126, v127
	v_cvt_pk_bf16_f32 v126, v120, v121
	v_add_f32_e32 v223, v223, v224
	v_and_b32_e32 v121, 64, v239
	v_mul_f32_e32 v224, v151, v151
	v_add_f32_e32 v148, v148, v149
	v_mul_f32_e32 v149, v123, v123
	v_xor_b32_e32 v120, 16, v239
	v_add_u32_e32 v121, 64, v121
	v_fmac_f32_e32 v224, v150, v150
	v_fmac_f32_e32 v149, v122, v122
	v_cmp_lt_i32_e32 vcc, v120, v121
	v_add_f32_e32 v223, v224, v223
	v_add_f32_e32 v148, v149, v148
	v_cndmask_b32_e32 v120, v239, v120, vcc
	v_add_f32_e32 v148, v223, v148
	v_cvt_pk_bf16_f32 v127, v122, v123
	global_store_dwordx4 v[200:201], v[124:127], off offset:256
	v_xor_b32_e32 v122, 32, v239
	v_cmp_lt_i32_e32 vcc, v122, v121
	v_lshlrev_b32_e32 v126, 2, v120
	v_mov_b32_e32 v120, v148
	s_nop 1
	v_permlane16_swap_b32_e32 v120, v148
	v_cndmask_b32_e32 v121, v239, v122, vcc
	v_lshlrev_b32_e32 v127, 2, v121
	s_waitcnt lgkmcnt(0)
	v_add_f32_e32 v120, v148, v120
	v_mov_b32_e32 v121, v120
	s_nop 1
	v_permlane32_swap_b32_e32 v121, v120
	s_and_saveexec_b64 s[46:47], s[38:39]
	s_cbranch_execz .LBB0_730
	v_lshlrev_b64 v[122:123], 7, v[190:191]
	v_lshl_add_u64 v[122:123], s[94:95], 0, v[122:123]
	v_lshl_add_u64 v[122:123], s[42:43], 2, v[122:123]
	s_lshl_b32 s30, s57, 2
	v_lshl_add_u64 v[122:123], v[122:123], 0, s[30:31]
	s_waitcnt lgkmcnt(0)
	v_add_f32_e32 v120, v120, v121
	global_store_dword v[122:123], v120, off
.LBB0_730:
	s_or_b64 exec, exec, s[46:47]
	s_waitcnt vmcnt(14)
	v_pk_add_f32 v[110:111], v[110:111], v[178:179]
	v_pk_add_f32 v[108:109], v[108:109], v[176:177]
	v_mul_f32_e32 v125, v111, v111
	v_mul_f32_e32 v124, v109, v109
	s_waitcnt lgkmcnt(0)
	v_lshl_add_u64 v[120:121], s[82:83], 0, v[218:219]
	v_pk_add_f32 v[104:105], v[104:105], v[172:173]
	v_fmac_f32_e32 v124, v108, v108
	v_fmac_f32_e32 v125, v110, v110
	v_lshl_add_u64 v[120:121], v[188:189], 2, v[120:121]
	v_add_f32_e32 v124, v124, v125
	v_mul_f32_e32 v125, v105, v105
	v_pk_add_f32 v[102:103], v[102:103], v[170:171]
	v_pk_add_f32 v[100:101], v[100:101], v[168:169]
	v_pk_add_f32 v[106:107], v[106:107], v[174:175]
	global_store_dwordx4 v[120:121], v[108:111], off
	global_store_dwordx4 v[120:121], v[104:107], off offset:16
	v_fmac_f32_e32 v125, v104, v104
	v_cvt_pk_bf16_f32 v108, v108, v109
	v_cvt_pk_bf16_f32 v109, v110, v111
	v_cvt_pk_bf16_f32 v110, v104, v105
	v_add_f32_e32 v124, v124, v125
	v_pk_add_f32 v[104:105], v[96:97], v[164:165]
	v_mul_f32_e32 v96, v101, v101
	v_mul_f32_e32 v97, v103, v103
	v_fmac_f32_e32 v96, v100, v100
	v_fmac_f32_e32 v97, v102, v102
	v_mul_f32_e32 v125, v107, v107
	v_add_f32_e32 v96, v96, v97
	v_mul_f32_e32 v97, v105, v105
	v_fmac_f32_e32 v125, v106, v106
	v_cvt_pk_bf16_f32 v111, v106, v107
	v_pk_add_f32 v[106:107], v[98:99], v[166:167]
	v_fmac_f32_e32 v97, v104, v104
	v_add_f32_e32 v96, v96, v97
	v_mul_f32_e32 v97, v107, v107
	v_fmac_f32_e32 v97, v106, v106
	v_add_f32_e32 v124, v125, v124
	v_add_f32_e32 v96, v97, v96
	v_add_f32_e32 v96, v124, v96
	v_mov_b32_e32 v97, v96
	s_nop 1
	v_permlane16_swap_b32_e32 v97, v96
	v_mov_b64_e32 v[122:123], s[4:5]
	v_mad_i64_i32 v[122:123], s[12:13], v214, s66, v[122:123]
	v_lshl_add_u64 v[122:123], v[188:189], 1, v[122:123]
	s_waitcnt lgkmcnt(0)
	v_add_f32_e32 v96, v96, v97
	v_mov_b32_e32 v97, v96
	s_nop 1
	v_permlane32_swap_b32_e32 v97, v96
	global_store_dwordx4 v[122:123], v[108:111], off
	global_store_dwordx4 v[120:121], v[100:103], off offset:512
	global_store_dwordx4 v[120:121], v[104:107], off offset:528
	v_cvt_pk_bf16_f32 v98, v100, v101
	v_cvt_pk_bf16_f32 v99, v102, v103
	s_nop 0
	v_cvt_pk_bf16_f32 v100, v104, v105
	v_cvt_pk_bf16_f32 v101, v106, v107
	global_store_dwordx4 v[122:123], v[98:101], off offset:256
	s_and_saveexec_b64 s[46:47], s[38:39]
	s_cbranch_execz .LBB0_732
	v_lshlrev_b64 v[98:99], 7, v[214:215]
	v_lshl_add_u64 v[98:99], s[94:95], 0, v[98:99]
	v_lshl_add_u64 v[98:99], s[42:43], 2, v[98:99]
	s_lshl_b32 s30, s57, 2
	v_lshl_add_u64 v[98:99], v[98:99], 0, s[30:31]
	s_waitcnt lgkmcnt(0)
	v_add_f32_e32 v96, v96, v97
	global_store_dword v[98:99], v96, off
.LBB0_732:
	s_or_b64 exec, exec, s[46:47]
	s_waitcnt vmcnt(16)
	v_pk_add_f32 v[94:95], v[94:95], v[162:163]
	v_pk_add_f32 v[92:93], v[92:93], v[160:161]
	v_mul_f32_e32 v101, v95, v95
	v_mul_f32_e32 v100, v93, v93
	s_waitcnt lgkmcnt(0)
	v_lshl_add_u64 v[96:97], s[82:83], 0, v[216:217]
	v_pk_add_f32 v[88:89], v[88:89], v[156:157]
	v_fmac_f32_e32 v100, v92, v92
	v_fmac_f32_e32 v101, v94, v94
	v_lshl_add_u64 v[96:97], v[188:189], 2, v[96:97]
	v_add_f32_e32 v100, v100, v101
	v_mul_f32_e32 v101, v89, v89
	v_pk_add_f32 v[86:87], v[86:87], v[146:147]
	v_pk_add_f32 v[84:85], v[84:85], v[144:145]
	v_pk_add_f32 v[90:91], v[90:91], v[158:159]
	global_store_dwordx4 v[96:97], v[92:95], off
	global_store_dwordx4 v[96:97], v[88:91], off offset:16
	v_fmac_f32_e32 v101, v88, v88
	v_cvt_pk_bf16_f32 v92, v92, v93
	v_cvt_pk_bf16_f32 v93, v94, v95
	v_cvt_pk_bf16_f32 v94, v88, v89
	v_add_f32_e32 v100, v100, v101
	v_pk_add_f32 v[88:89], v[80:81], v[128:129]
	v_mul_f32_e32 v80, v85, v85
	v_mul_f32_e32 v81, v87, v87
	v_fmac_f32_e32 v80, v84, v84
	v_fmac_f32_e32 v81, v86, v86
	v_mul_f32_e32 v101, v91, v91
	v_add_f32_e32 v80, v80, v81
	v_mul_f32_e32 v81, v89, v89
	v_fmac_f32_e32 v101, v90, v90
	v_cvt_pk_bf16_f32 v95, v90, v91
	v_pk_add_f32 v[90:91], v[82:83], v[130:131]
	v_fmac_f32_e32 v81, v88, v88
	v_add_f32_e32 v80, v80, v81
	v_mul_f32_e32 v81, v91, v91
	v_fmac_f32_e32 v81, v90, v90
	v_add_f32_e32 v100, v101, v100
	v_add_f32_e32 v80, v81, v80
	v_add_f32_e32 v80, v100, v80
	v_mov_b32_e32 v81, v80
	s_nop 1
	v_permlane16_swap_b32_e32 v81, v80
	v_mov_b64_e32 v[98:99], s[4:5]
	v_mad_i64_i32 v[98:99], s[12:13], v210, s66, v[98:99]
	v_lshl_add_u64 v[98:99], v[188:189], 1, v[98:99]
	s_waitcnt lgkmcnt(0)
	v_add_f32_e32 v80, v80, v81
	v_mov_b32_e32 v81, v80
	s_nop 1
	v_permlane32_swap_b32_e32 v81, v80
	global_store_dwordx4 v[98:99], v[92:95], off
	global_store_dwordx4 v[96:97], v[84:87], off offset:512
	global_store_dwordx4 v[96:97], v[88:91], off offset:528
	v_cvt_pk_bf16_f32 v82, v84, v85
	v_cvt_pk_bf16_f32 v83, v86, v87
	s_nop 0
	v_cvt_pk_bf16_f32 v84, v88, v89
	v_cvt_pk_bf16_f32 v85, v90, v91
	global_store_dwordx4 v[98:99], v[82:85], off offset:256
	s_and_saveexec_b64 s[46:47], s[38:39]
	s_cbranch_execz .LBB0_734
	v_lshlrev_b64 v[82:83], 7, v[210:211]
	v_lshl_add_u64 v[82:83], s[94:95], 0, v[82:83]
	v_lshl_add_u64 v[82:83], s[42:43], 2, v[82:83]
	s_lshl_b32 s30, s57, 2
	v_lshl_add_u64 v[82:83], v[82:83], 0, s[30:31]
	s_waitcnt lgkmcnt(0)
	v_add_f32_e32 v80, v80, v81
	global_store_dword v[82:83], v80, off
.LBB0_734:
	s_or_b64 exec, exec, s[46:47]
	s_waitcnt vmcnt(18)
	v_pk_add_f32 v[78:79], v[78:79], v[142:143]
	v_pk_add_f32 v[76:77], v[76:77], v[140:141]
	v_mul_f32_e32 v85, v79, v79
	v_mul_f32_e32 v84, v77, v77
	s_waitcnt lgkmcnt(0)
	v_lshl_add_u64 v[80:81], s[82:83], 0, v[212:213]
	v_pk_add_f32 v[72:73], v[72:73], v[132:133]
	v_fmac_f32_e32 v84, v76, v76
	v_fmac_f32_e32 v85, v78, v78
	v_lshl_add_u64 v[80:81], v[188:189], 2, v[80:81]
	v_add_f32_e32 v84, v84, v85
	v_mul_f32_e32 v85, v73, v73
	v_pk_add_f32 v[70:71], v[70:71], v[118:119]
	v_pk_add_f32 v[68:69], v[68:69], v[116:117]
	v_pk_add_f32 v[74:75], v[74:75], v[134:135]
	global_store_dwordx4 v[80:81], v[76:79], off
	global_store_dwordx4 v[80:81], v[72:75], off offset:16
	v_fmac_f32_e32 v85, v72, v72
	v_cvt_pk_bf16_f32 v76, v76, v77
	v_cvt_pk_bf16_f32 v77, v78, v79
	v_cvt_pk_bf16_f32 v78, v72, v73
	v_add_f32_e32 v84, v84, v85
	v_pk_add_f32 v[72:73], v[64:65], v[112:113]
	v_mul_f32_e32 v64, v69, v69
	v_mul_f32_e32 v65, v71, v71
	v_fmac_f32_e32 v64, v68, v68
	v_fmac_f32_e32 v65, v70, v70
	v_mul_f32_e32 v85, v75, v75
	v_add_f32_e32 v64, v64, v65
	v_mul_f32_e32 v65, v73, v73
	v_fmac_f32_e32 v85, v74, v74
	v_cvt_pk_bf16_f32 v79, v74, v75
	v_pk_add_f32 v[74:75], v[66:67], v[114:115]
	v_fmac_f32_e32 v65, v72, v72
	v_add_f32_e32 v64, v64, v65
	v_mul_f32_e32 v65, v75, v75
	v_fmac_f32_e32 v65, v74, v74
	v_add_f32_e32 v84, v85, v84
	v_add_f32_e32 v64, v65, v64
	v_add_f32_e32 v64, v84, v64
	v_mov_b32_e32 v65, v64
	s_nop 1
	v_permlane16_swap_b32_e32 v65, v64
	v_mov_b64_e32 v[82:83], s[4:5]
	v_mad_i64_i32 v[82:83], s[12:13], v208, s66, v[82:83]
	v_lshl_add_u64 v[82:83], v[188:189], 1, v[82:83]
	s_waitcnt lgkmcnt(0)
	v_add_f32_e32 v64, v64, v65
	v_mov_b32_e32 v65, v64
	s_nop 1
	v_permlane32_swap_b32_e32 v65, v64
	global_store_dwordx4 v[82:83], v[76:79], off
	global_store_dwordx4 v[80:81], v[68:71], off offset:512
	global_store_dwordx4 v[80:81], v[72:75], off offset:528
	v_cvt_pk_bf16_f32 v66, v68, v69
	v_cvt_pk_bf16_f32 v67, v70, v71
	s_nop 0
	v_cvt_pk_bf16_f32 v68, v72, v73
	v_cvt_pk_bf16_f32 v69, v74, v75
	global_store_dwordx4 v[82:83], v[66:69], off offset:256
	s_and_saveexec_b64 s[46:47], s[38:39]
	s_cbranch_execz .LBB0_736
	v_lshlrev_b64 v[66:67], 7, v[208:209]
	v_lshl_add_u64 v[66:67], s[94:95], 0, v[66:67]
	v_lshl_add_u64 v[66:67], s[42:43], 2, v[66:67]
	s_lshl_b32 s30, s57, 2
	v_lshl_add_u64 v[66:67], v[66:67], 0, s[30:31]
	s_waitcnt lgkmcnt(0)
	v_add_f32_e32 v64, v64, v65
	global_store_dword v[66:67], v64, off
.LBB0_736:
	s_or_b64 exec, exec, s[46:47]
	v_add_u32_e32 v122, 0x80, v190
	v_ashrrev_i32_e32 v123, 31, v122
	v_lshlrev_b64 v[148:149], 13, v[122:123]
	s_waitcnt lgkmcnt(0)
	v_lshl_add_u64 v[64:65], v[206:207], 0, v[148:149]
	global_load_dwordx4 v[128:131], v[64:65], off
	global_load_dwordx4 v[132:135], v[64:65], off offset:16
	global_load_dwordx4 v[140:143], v[64:65], off offset:512
	global_load_dwordx4 v[144:147], v[64:65], off offset:528
	v_add_u32_e32 v118, 0x90, v190
	v_add_u32_e32 v114, 0xa0, v190
	v_add_u32_e32 v112, 0xb0, v190
	v_ashrrev_i32_e32 v119, 31, v118
	v_ashrrev_i32_e32 v115, 31, v114
	v_ashrrev_i32_e32 v113, 31, v112
	v_lshlrev_b64 v[124:125], 13, v[118:119]
	v_lshlrev_b64 v[120:121], 13, v[114:115]
	v_lshlrev_b64 v[116:117], 13, v[112:113]
	v_lshl_add_u64 v[64:65], v[206:207], 0, v[124:125]
	v_lshl_add_u64 v[66:67], v[206:207], 0, v[120:121]
	v_lshl_add_u64 v[68:69], v[206:207], 0, v[116:117]
	global_load_dwordx4 v[104:107], v[64:65], off offset:16
	global_load_dwordx4 v[108:111], v[64:65], off
	global_load_dwordx4 v[96:99], v[64:65], off offset:528
	global_load_dwordx4 v[100:103], v[64:65], off offset:512
	global_load_dwordx4 v[88:91], v[66:67], off offset:16
	global_load_dwordx4 v[92:95], v[66:67], off
	global_load_dwordx4 v[80:83], v[66:67], off offset:528
	global_load_dwordx4 v[84:87], v[66:67], off offset:512
	global_load_dwordx4 v[72:75], v[68:69], off offset:16
	global_load_dwordx4 v[76:79], v[68:69], off
	s_nop 0
	global_load_dwordx4 v[64:67], v[68:69], off offset:528
	s_nop 0
	global_load_dwordx4 v[68:71], v[68:69], off offset:512
	v_lshl_add_u64 v[148:149], s[82:83], 0, v[148:149]
	v_lshl_add_u64 v[148:149], v[188:189], 2, v[148:149]
	v_mov_b64_e32 v[150:151], s[4:5]
	v_mad_i64_i32 v[150:151], s[12:13], v122, s66, v[150:151]
	v_lshl_add_u64 v[150:151], v[188:189], 1, v[150:151]
	s_waitcnt vmcnt(15)
	v_pk_add_f32 v[62:63], v[62:63], v[130:131]
	v_pk_add_f32 v[60:61], v[60:61], v[128:129]
	s_waitcnt vmcnt(14)
	v_pk_add_f32 v[58:59], v[58:59], v[134:135]
	v_pk_add_f32 v[56:57], v[56:57], v[132:133]
	s_waitcnt vmcnt(13)
	v_pk_add_f32 v[54:55], v[54:55], v[142:143]
	v_pk_add_f32 v[52:53], v[52:53], v[140:141]
	s_waitcnt vmcnt(12)
	v_pk_add_f32 v[130:131], v[50:51], v[146:147]
	v_pk_add_f32 v[128:129], v[48:49], v[144:145]
	global_store_dwordx4 v[148:149], v[60:63], off
	global_store_dwordx4 v[148:149], v[56:59], off offset:16
	v_mul_f32_e32 v132, v61, v61
	v_mul_f32_e32 v133, v63, v63
	v_mul_f32_e32 v134, v57, v57
	v_mul_f32_e32 v135, v59, v59
	v_cvt_pk_bf16_f32 v48, v60, v61
	v_cvt_pk_bf16_f32 v49, v62, v63
	v_cvt_pk_bf16_f32 v50, v56, v57
	v_cvt_pk_bf16_f32 v51, v58, v59
	v_mul_f32_e32 v57, v53, v53
	v_mul_f32_e32 v59, v55, v55
	v_mul_f32_e32 v61, v129, v129
	v_fmac_f32_e32 v132, v60, v60
	v_fmac_f32_e32 v133, v62, v62
	v_fmac_f32_e32 v57, v52, v52
	v_fmac_f32_e32 v59, v54, v54
	v_mul_f32_e32 v63, v131, v131
	v_fmac_f32_e32 v134, v56, v56
	v_fmac_f32_e32 v61, v128, v128
	v_add_f32_e32 v56, v132, v133
	v_add_f32_e32 v57, v57, v59
	v_fmac_f32_e32 v135, v58, v58
	v_fmac_f32_e32 v63, v130, v130
	v_add_f32_e32 v56, v56, v134
	v_add_f32_e32 v57, v57, v61
	v_add_f32_e32 v56, v135, v56
	v_add_f32_e32 v57, v63, v57
	v_add_f32_e32 v56, v56, v57
	v_mov_b32_e32 v57, v56
	s_nop 1
	v_permlane16_swap_b32_e32 v57, v56
	global_store_dwordx4 v[150:151], v[48:51], off
	global_store_dwordx4 v[148:149], v[52:55], off offset:512
	global_store_dwordx4 v[148:149], v[128:131], off offset:528
	v_cvt_pk_bf16_f32 v50, v52, v53
	v_cvt_pk_bf16_f32 v51, v54, v55
	s_waitcnt lgkmcnt(0)
	v_add_f32_e32 v48, v56, v57
	v_mov_b32_e32 v49, v48
	s_nop 1
	v_permlane32_swap_b32_e32 v49, v48
	v_cvt_pk_bf16_f32 v52, v128, v129
	v_cvt_pk_bf16_f32 v53, v130, v131
	global_store_dwordx4 v[150:151], v[50:53], off offset:256
	s_and_saveexec_b64 s[46:47], s[38:39]
	s_cbranch_execz .LBB0_738
	v_lshlrev_b64 v[50:51], 7, v[122:123]
	v_lshl_add_u64 v[50:51], s[94:95], 0, v[50:51]
	v_lshl_add_u64 v[50:51], s[42:43], 2, v[50:51]
	s_lshl_b32 s30, s57, 2
	v_lshl_add_u64 v[50:51], v[50:51], 0, s[30:31]
	s_waitcnt lgkmcnt(0)
	v_add_f32_e32 v48, v48, v49
	global_store_dword v[50:51], v48, off
.LBB0_738:
	s_or_b64 exec, exec, s[46:47]
	s_waitcnt vmcnt(16)
	v_pk_add_f32 v[46:47], v[46:47], v[110:111]
	v_pk_add_f32 v[44:45], v[44:45], v[108:109]
	v_mul_f32_e32 v53, v47, v47
	v_mul_f32_e32 v52, v45, v45
	s_waitcnt lgkmcnt(0)
	v_lshl_add_u64 v[48:49], s[82:83], 0, v[124:125]
	v_pk_add_f32 v[40:41], v[40:41], v[104:105]
	v_fmac_f32_e32 v52, v44, v44
	v_fmac_f32_e32 v53, v46, v46
	v_lshl_add_u64 v[48:49], v[188:189], 2, v[48:49]
	v_add_f32_e32 v52, v52, v53
	v_mul_f32_e32 v53, v41, v41
	s_waitcnt vmcnt(14)
	v_pk_add_f32 v[38:39], v[38:39], v[102:103]
	v_pk_add_f32 v[36:37], v[36:37], v[100:101]
	v_pk_add_f32 v[42:43], v[42:43], v[106:107]
	global_store_dwordx4 v[48:49], v[44:47], off
	global_store_dwordx4 v[48:49], v[40:43], off offset:16
	v_fmac_f32_e32 v53, v40, v40
	v_cvt_pk_bf16_f32 v44, v44, v45
	v_cvt_pk_bf16_f32 v45, v46, v47
	v_cvt_pk_bf16_f32 v46, v40, v41
	v_add_f32_e32 v52, v52, v53
	v_pk_add_f32 v[40:41], v[32:33], v[96:97]
	v_mul_f32_e32 v32, v37, v37
	v_mul_f32_e32 v33, v39, v39
	v_fmac_f32_e32 v32, v36, v36
	v_fmac_f32_e32 v33, v38, v38
	v_mul_f32_e32 v53, v43, v43
	v_add_f32_e32 v32, v32, v33
	v_mul_f32_e32 v33, v41, v41
	v_fmac_f32_e32 v53, v42, v42
	v_cvt_pk_bf16_f32 v47, v42, v43
	v_pk_add_f32 v[42:43], v[34:35], v[98:99]
	v_fmac_f32_e32 v33, v40, v40
	v_add_f32_e32 v32, v32, v33
	v_mul_f32_e32 v33, v43, v43
	v_fmac_f32_e32 v33, v42, v42
	v_add_f32_e32 v52, v53, v52
	v_add_f32_e32 v32, v33, v32
	v_add_f32_e32 v32, v52, v32
	v_mov_b32_e32 v33, v32
	s_nop 1
	v_permlane16_swap_b32_e32 v33, v32
	v_mov_b64_e32 v[50:51], s[4:5]
	v_mad_i64_i32 v[50:51], s[12:13], v118, s66, v[50:51]
	v_lshl_add_u64 v[50:51], v[188:189], 1, v[50:51]
	s_waitcnt lgkmcnt(0)
	v_add_f32_e32 v32, v32, v33
	v_mov_b32_e32 v33, v32
	s_nop 1
	v_permlane32_swap_b32_e32 v33, v32
	global_store_dwordx4 v[50:51], v[44:47], off
	global_store_dwordx4 v[48:49], v[36:39], off offset:512
	global_store_dwordx4 v[48:49], v[40:43], off offset:528
	v_cvt_pk_bf16_f32 v34, v36, v37
	v_cvt_pk_bf16_f32 v35, v38, v39
	s_nop 0
	v_cvt_pk_bf16_f32 v36, v40, v41
	v_cvt_pk_bf16_f32 v37, v42, v43
	global_store_dwordx4 v[50:51], v[34:37], off offset:256
	s_and_saveexec_b64 s[46:47], s[38:39]
	s_cbranch_execz .LBB0_740
	v_lshlrev_b64 v[34:35], 7, v[118:119]
	v_lshl_add_u64 v[34:35], s[94:95], 0, v[34:35]
	v_lshl_add_u64 v[34:35], s[42:43], 2, v[34:35]
	s_lshl_b32 s30, s57, 2
	v_lshl_add_u64 v[34:35], v[34:35], 0, s[30:31]
	s_waitcnt lgkmcnt(0)
	v_add_f32_e32 v32, v32, v33
	global_store_dword v[34:35], v32, off
.LBB0_740:
	s_or_b64 exec, exec, s[46:47]
	s_waitcnt vmcnt(18)
	v_pk_add_f32 v[30:31], v[30:31], v[94:95]
	v_pk_add_f32 v[28:29], v[28:29], v[92:93]
	v_mul_f32_e32 v37, v31, v31
	v_mul_f32_e32 v36, v29, v29
	s_waitcnt lgkmcnt(0)
	v_lshl_add_u64 v[32:33], s[82:83], 0, v[120:121]
	v_pk_add_f32 v[24:25], v[24:25], v[88:89]
	v_fmac_f32_e32 v36, v28, v28
	v_fmac_f32_e32 v37, v30, v30
	v_lshl_add_u64 v[32:33], v[188:189], 2, v[32:33]
	v_add_f32_e32 v36, v36, v37
	v_mul_f32_e32 v37, v25, v25
	s_waitcnt vmcnt(16)
	v_pk_add_f32 v[22:23], v[22:23], v[86:87]
	v_pk_add_f32 v[20:21], v[20:21], v[84:85]
	v_pk_add_f32 v[26:27], v[26:27], v[90:91]
	global_store_dwordx4 v[32:33], v[28:31], off
	global_store_dwordx4 v[32:33], v[24:27], off offset:16
	v_fmac_f32_e32 v37, v24, v24
	v_cvt_pk_bf16_f32 v28, v28, v29
	v_cvt_pk_bf16_f32 v29, v30, v31
	v_cvt_pk_bf16_f32 v30, v24, v25
	v_add_f32_e32 v36, v36, v37
	v_pk_add_f32 v[24:25], v[16:17], v[80:81]
	v_mul_f32_e32 v16, v21, v21
	v_mul_f32_e32 v17, v23, v23
	v_fmac_f32_e32 v16, v20, v20
	v_fmac_f32_e32 v17, v22, v22
	v_mul_f32_e32 v37, v27, v27
	v_add_f32_e32 v16, v16, v17
	v_mul_f32_e32 v17, v25, v25
	v_fmac_f32_e32 v37, v26, v26
	v_cvt_pk_bf16_f32 v31, v26, v27
	v_pk_add_f32 v[26:27], v[18:19], v[82:83]
	v_fmac_f32_e32 v17, v24, v24
	v_add_f32_e32 v16, v16, v17
	v_mul_f32_e32 v17, v27, v27
	v_fmac_f32_e32 v17, v26, v26
	v_add_f32_e32 v36, v37, v36
	v_add_f32_e32 v16, v17, v16
	v_add_f32_e32 v16, v36, v16
	v_mov_b32_e32 v17, v16
	s_nop 1
	v_permlane16_swap_b32_e32 v17, v16
	v_mov_b64_e32 v[34:35], s[4:5]
	v_mad_i64_i32 v[34:35], s[12:13], v114, s66, v[34:35]
	v_lshl_add_u64 v[34:35], v[188:189], 1, v[34:35]
	s_waitcnt lgkmcnt(0)
	v_add_f32_e32 v16, v16, v17
	v_mov_b32_e32 v17, v16
	s_nop 1
	v_permlane32_swap_b32_e32 v17, v16
	global_store_dwordx4 v[34:35], v[28:31], off
	global_store_dwordx4 v[32:33], v[20:23], off offset:512
	global_store_dwordx4 v[32:33], v[24:27], off offset:528
	v_cvt_pk_bf16_f32 v18, v20, v21
	v_cvt_pk_bf16_f32 v19, v22, v23
	s_nop 0
	v_cvt_pk_bf16_f32 v20, v24, v25
	v_cvt_pk_bf16_f32 v21, v26, v27
	global_store_dwordx4 v[34:35], v[18:21], off offset:256
	s_and_saveexec_b64 s[46:47], s[38:39]
	s_cbranch_execz .LBB0_742
	v_lshlrev_b64 v[18:19], 7, v[114:115]
	v_lshl_add_u64 v[18:19], s[94:95], 0, v[18:19]
	v_lshl_add_u64 v[18:19], s[42:43], 2, v[18:19]
	s_lshl_b32 s30, s57, 2
	v_lshl_add_u64 v[18:19], v[18:19], 0, s[30:31]
	s_waitcnt lgkmcnt(0)
	v_add_f32_e32 v16, v16, v17
	global_store_dword v[18:19], v16, off
.LBB0_742:
	s_or_b64 exec, exec, s[46:47]
	s_waitcnt vmcnt(20)
	v_pk_add_f32 v[14:15], v[14:15], v[78:79]
	v_pk_add_f32 v[12:13], v[12:13], v[76:77]
	v_mul_f32_e32 v21, v15, v15
	v_mul_f32_e32 v20, v13, v13
	s_waitcnt lgkmcnt(0)
	v_lshl_add_u64 v[16:17], s[82:83], 0, v[116:117]
	v_pk_add_f32 v[8:9], v[8:9], v[72:73]
	v_fmac_f32_e32 v20, v12, v12
	v_fmac_f32_e32 v21, v14, v14
	v_lshl_add_u64 v[16:17], v[188:189], 2, v[16:17]
	v_add_f32_e32 v20, v20, v21
	v_mul_f32_e32 v21, v9, v9
	s_waitcnt vmcnt(18)
	v_pk_add_f32 v[6:7], v[6:7], v[70:71]
	v_pk_add_f32 v[4:5], v[4:5], v[68:69]
	v_pk_add_f32 v[10:11], v[10:11], v[74:75]
	global_store_dwordx4 v[16:17], v[12:15], off
	global_store_dwordx4 v[16:17], v[8:11], off offset:16
	v_fmac_f32_e32 v21, v8, v8
	v_cvt_pk_bf16_f32 v12, v12, v13
	v_cvt_pk_bf16_f32 v13, v14, v15
	v_cvt_pk_bf16_f32 v14, v8, v9
	v_add_f32_e32 v20, v20, v21
	v_pk_add_f32 v[8:9], v[0:1], v[64:65]
	v_mul_f32_e32 v0, v5, v5
	v_mul_f32_e32 v1, v7, v7
	v_fmac_f32_e32 v0, v4, v4
	v_fmac_f32_e32 v1, v6, v6
	v_mul_f32_e32 v21, v11, v11
	v_add_f32_e32 v0, v0, v1
	v_mul_f32_e32 v1, v9, v9
	v_fmac_f32_e32 v21, v10, v10
	v_cvt_pk_bf16_f32 v15, v10, v11
	v_pk_add_f32 v[10:11], v[2:3], v[66:67]
	v_fmac_f32_e32 v1, v8, v8
	v_add_f32_e32 v0, v0, v1
	v_mul_f32_e32 v1, v11, v11
	v_fmac_f32_e32 v1, v10, v10
	v_add_f32_e32 v20, v21, v20
	v_add_f32_e32 v0, v1, v0
	v_add_f32_e32 v0, v20, v0
	v_mov_b32_e32 v1, v0
	s_nop 1
	v_permlane16_swap_b32_e32 v1, v0
	v_mov_b64_e32 v[18:19], s[4:5]
	v_mad_i64_i32 v[18:19], s[12:13], v112, s66, v[18:19]
	v_lshl_add_u64 v[18:19], v[188:189], 1, v[18:19]
	s_waitcnt lgkmcnt(0)
	v_add_f32_e32 v0, v0, v1
	v_mov_b32_e32 v1, v0
	s_nop 1
	v_permlane32_swap_b32_e32 v1, v0
	global_store_dwordx4 v[18:19], v[12:15], off
	global_store_dwordx4 v[16:17], v[4:7], off offset:512
	global_store_dwordx4 v[16:17], v[8:11], off offset:528
	v_cvt_pk_bf16_f32 v2, v4, v5
	v_cvt_pk_bf16_f32 v3, v6, v7
	s_nop 0
	v_cvt_pk_bf16_f32 v4, v8, v9
	v_cvt_pk_bf16_f32 v5, v10, v11
	global_store_dwordx4 v[18:19], v[2:5], off offset:256
	s_and_saveexec_b64 s[46:47], s[38:39]
	s_cbranch_execz .LBB0_717
	v_lshlrev_b64 v[2:3], 7, v[112:113]
	v_lshl_add_u64 v[2:3], s[94:95], 0, v[2:3]
	v_lshl_add_u64 v[2:3], s[42:43], 2, v[2:3]
	s_lshl_b32 s30, s57, 2
	v_lshl_add_u64 v[2:3], v[2:3], 0, s[30:31]
	s_waitcnt lgkmcnt(0)
	v_add_f32_e32 v0, v0, v1
	global_store_dword v[2:3], v0, off
	s_branch .LBB0_717

.LBB0_932:
	v_mul_f32_e32 v117, v117, v117
	v_fmac_f32_e32 v117, v116, v116
	v_mul_f32_e32 v116, v119, v119
	v_mul_f32_e32 v125, v125, v125
	v_fmac_f32_e32 v116, v118, v118
	v_mul_f32_e32 v113, v113, v113
	v_fmac_f32_e32 v125, v124, v124
	v_mul_f32_e32 v124, v127, v127
	v_add_f32_e32 v116, v117, v116
	v_fmac_f32_e32 v113, v112, v112
	v_fmac_f32_e32 v124, v126, v126
	v_mul_f32_e32 v121, v121, v121
	v_add_f32_e32 v112, v116, v113
	v_mul_f32_e32 v113, v115, v115
	v_add_f32_e32 v124, v125, v124
	v_fmac_f32_e32 v121, v120, v120
	v_fmac_f32_e32 v113, v114, v114
	v_and_b32_e32 v114, 64, v239
	v_add_f32_e32 v120, v124, v121
	v_mul_f32_e32 v121, v123, v123
	v_add_f32_e32 v112, v113, v112
	v_xor_b32_e32 v113, 16, v239
	v_add_u32_e32 v114, 64, v114
	v_fmac_f32_e32 v121, v122, v122
	v_cmp_lt_i32_e32 vcc, v113, v114
	v_add_f32_e32 v120, v121, v120
	v_add_f32_e32 v112, v120, v112
	v_cndmask_b32_e32 v113, v239, v113, vcc
	v_lshlrev_b32_e32 v180, 2, v113
	v_mov_b32_e32 v113, v112
	s_nop 1
	v_permlane16_swap_b32_e32 v113, v112
	s_lshl_b32 s48, s74, 2
	s_ashr_i32 s49, s48, 31
	s_waitcnt lgkmcnt(0)
	v_add_f32_e32 v112, v112, v113
	v_xor_b32_e32 v113, 32, v239
	v_cmp_lt_i32_e32 vcc, v113, v114
	s_nop 1
	v_cndmask_b32_e32 v113, v239, v113, vcc
	v_lshlrev_b32_e32 v181, 2, v113
	v_mov_b32_e32 v113, v112
	s_nop 1
	v_permlane32_swap_b32_e32 v113, v112
	s_and_saveexec_b64 s[50:51], s[42:43]
	s_cbranch_execz .LBB0_934
	v_lshlrev_b64 v[114:115], 7, v[216:217]
	v_lshl_add_u64 v[114:115], s[94:95], 0, v[114:115]
	v_lshl_add_u64 v[114:115], s[48:49], 2, v[114:115]
	s_lshl_b32 s30, s56, 2
	v_lshl_add_u64 v[114:115], v[114:115], 0, s[30:31]
	s_waitcnt lgkmcnt(0)
	v_add_f32_e32 v112, v112, v113
	global_store_dword v[114:115], v112, off

.LBB0_938:
	v_mul_f32_e32 v109, v109, v109
	v_mul_f32_e32 v101, v101, v101
	v_fmac_f32_e32 v109, v108, v108
	v_mul_f32_e32 v108, v111, v111
	v_fmac_f32_e32 v101, v100, v100
	v_mul_f32_e32 v100, v103, v103
	v_fmac_f32_e32 v108, v110, v110
	v_mul_f32_e32 v105, v105, v105
	v_fmac_f32_e32 v100, v102, v102
	v_mul_f32_e32 v97, v97, v97
	v_add_f32_e32 v108, v109, v108
	v_fmac_f32_e32 v105, v104, v104
	v_add_f32_e32 v100, v101, v100
	v_fmac_f32_e32 v97, v96, v96
	v_add_f32_e32 v104, v108, v105
	v_mul_f32_e32 v105, v107, v107
	v_add_f32_e32 v96, v100, v97
	v_mul_f32_e32 v97, v99, v99
	v_fmac_f32_e32 v105, v106, v106
	v_fmac_f32_e32 v97, v98, v98
	v_add_f32_e32 v104, v105, v104
	v_add_f32_e32 v96, v97, v96
	v_add_f32_e32 v96, v104, v96
	v_mov_b32_e32 v97, v96
	s_nop 1
	v_permlane16_swap_b32_e32 v97, v96
	s_waitcnt lgkmcnt(0)
	v_add_f32_e32 v96, v96, v97
	v_mov_b32_e32 v97, v96
	s_nop 1
	v_permlane32_swap_b32_e32 v97, v96
	s_and_saveexec_b64 s[50:51], s[42:43]
	s_cbranch_execz .LBB0_940
	v_lshlrev_b64 v[98:99], 7, v[226:227]
	v_lshl_add_u64 v[98:99], s[94:95], 0, v[98:99]
	v_lshl_add_u64 v[98:99], s[48:49], 2, v[98:99]
	s_lshl_b32 s30, s56, 2
	v_lshl_add_u64 v[98:99], v[98:99], 0, s[30:31]
	s_waitcnt lgkmcnt(0)
	v_add_f32_e32 v96, v96, v97
	global_store_dword v[98:99], v96, off

.LBB0_944:
	v_mul_f32_e32 v93, v93, v93
	v_mul_f32_e32 v85, v85, v85
	v_fmac_f32_e32 v93, v92, v92
	v_mul_f32_e32 v92, v95, v95
	v_fmac_f32_e32 v85, v84, v84
	v_mul_f32_e32 v84, v87, v87
	v_fmac_f32_e32 v92, v94, v94
	v_mul_f32_e32 v89, v89, v89
	v_fmac_f32_e32 v84, v86, v86
	v_mul_f32_e32 v81, v81, v81
	v_add_f32_e32 v92, v93, v92
	v_fmac_f32_e32 v89, v88, v88
	v_add_f32_e32 v84, v85, v84
	v_fmac_f32_e32 v81, v80, v80
	v_add_f32_e32 v88, v92, v89
	v_mul_f32_e32 v89, v91, v91
	v_add_f32_e32 v80, v84, v81
	v_mul_f32_e32 v81, v83, v83
	v_fmac_f32_e32 v89, v90, v90
	v_fmac_f32_e32 v81, v82, v82
	v_add_f32_e32 v88, v89, v88
	v_add_f32_e32 v80, v81, v80
	v_add_f32_e32 v80, v88, v80
	v_mov_b32_e32 v81, v80
	s_nop 1
	v_permlane16_swap_b32_e32 v81, v80
	s_waitcnt lgkmcnt(0)
	v_add_f32_e32 v80, v80, v81
	v_mov_b32_e32 v81, v80
	s_nop 1
	v_permlane32_swap_b32_e32 v81, v80
	s_and_saveexec_b64 s[50:51], s[42:43]
	s_cbranch_execz .LBB0_946
	v_lshlrev_b64 v[82:83], 7, v[222:223]
	v_lshl_add_u64 v[82:83], s[94:95], 0, v[82:83]
	v_lshl_add_u64 v[82:83], s[48:49], 2, v[82:83]
	s_lshl_b32 s30, s56, 2
	v_lshl_add_u64 v[82:83], v[82:83], 0, s[30:31]
	s_waitcnt lgkmcnt(0)
	v_add_f32_e32 v80, v80, v81
	global_store_dword v[82:83], v80, off

.LBB0_950:
	v_mul_f32_e32 v77, v77, v77
	v_mul_f32_e32 v69, v69, v69
	v_fmac_f32_e32 v77, v76, v76
	v_mul_f32_e32 v76, v79, v79
	v_fmac_f32_e32 v69, v68, v68
	v_mul_f32_e32 v68, v71, v71
	v_fmac_f32_e32 v76, v78, v78
	v_mul_f32_e32 v73, v73, v73
	v_fmac_f32_e32 v68, v70, v70
	v_mul_f32_e32 v65, v65, v65
	v_add_f32_e32 v76, v77, v76
	v_fmac_f32_e32 v73, v72, v72
	v_add_f32_e32 v68, v69, v68
	v_fmac_f32_e32 v65, v64, v64
	v_add_f32_e32 v72, v76, v73
	v_mul_f32_e32 v73, v75, v75
	v_add_f32_e32 v64, v68, v65
	v_mul_f32_e32 v65, v67, v67
	v_fmac_f32_e32 v73, v74, v74
	v_fmac_f32_e32 v65, v66, v66
	v_add_f32_e32 v72, v73, v72
	v_add_f32_e32 v64, v65, v64
	v_add_f32_e32 v64, v72, v64
	v_mov_b32_e32 v65, v64
	s_nop 1
	v_permlane16_swap_b32_e32 v65, v64
	s_waitcnt lgkmcnt(0)
	v_add_f32_e32 v64, v64, v65
	v_mov_b32_e32 v65, v64
	s_nop 1
	v_permlane32_swap_b32_e32 v65, v64
	s_and_saveexec_b64 s[50:51], s[42:43]
	s_cbranch_execz .LBB0_952
	v_lshlrev_b64 v[66:67], 7, v[220:221]
	v_lshl_add_u64 v[66:67], s[94:95], 0, v[66:67]
	v_lshl_add_u64 v[66:67], s[48:49], 2, v[66:67]
	s_lshl_b32 s30, s56, 2
	v_lshl_add_u64 v[66:67], v[66:67], 0, s[30:31]
	s_waitcnt lgkmcnt(0)
	v_add_f32_e32 v64, v64, v65
	global_store_dword v[66:67], v64, off

.LBB0_956:
	v_mul_f32_e32 v61, v61, v61
	v_mul_f32_e32 v53, v53, v53
	v_fmac_f32_e32 v61, v60, v60
	v_mul_f32_e32 v60, v63, v63
	v_fmac_f32_e32 v53, v52, v52
	v_mul_f32_e32 v52, v55, v55
	v_fmac_f32_e32 v60, v62, v62
	v_mul_f32_e32 v57, v57, v57
	v_fmac_f32_e32 v52, v54, v54
	v_mul_f32_e32 v49, v49, v49
	v_add_f32_e32 v60, v61, v60
	v_fmac_f32_e32 v57, v56, v56
	v_add_f32_e32 v52, v53, v52
	v_fmac_f32_e32 v49, v48, v48
	v_add_f32_e32 v56, v60, v57
	v_mul_f32_e32 v57, v59, v59
	v_add_f32_e32 v48, v52, v49
	v_mul_f32_e32 v49, v51, v51
	v_fmac_f32_e32 v57, v58, v58
	v_fmac_f32_e32 v49, v50, v50
	v_add_f32_e32 v56, v57, v56
	v_add_f32_e32 v48, v49, v48
	v_add_f32_e32 v48, v56, v48
	v_mov_b32_e32 v49, v48
	s_nop 1
	v_permlane16_swap_b32_e32 v49, v48
	s_waitcnt lgkmcnt(0)
	v_add_f32_e32 v48, v48, v49
	v_mov_b32_e32 v49, v48
	s_nop 1
	v_permlane32_swap_b32_e32 v49, v48
	s_and_saveexec_b64 s[50:51], s[42:43]
	s_cbranch_execz .LBB0_958
	v_lshlrev_b64 v[50:51], 7, v[134:135]
	v_lshl_add_u64 v[50:51], s[94:95], 0, v[50:51]
	v_lshl_add_u64 v[50:51], s[48:49], 2, v[50:51]
	s_lshl_b32 s30, s56, 2
	v_lshl_add_u64 v[50:51], v[50:51], 0, s[30:31]
	s_waitcnt lgkmcnt(0)
	v_add_f32_e32 v48, v48, v49
	global_store_dword v[50:51], v48, off

.LBB0_962:
	v_mul_f32_e32 v45, v45, v45
	v_mul_f32_e32 v37, v37, v37
	v_fmac_f32_e32 v45, v44, v44
	v_mul_f32_e32 v44, v47, v47
	v_fmac_f32_e32 v37, v36, v36
	v_mul_f32_e32 v36, v39, v39
	v_fmac_f32_e32 v44, v46, v46
	v_mul_f32_e32 v41, v41, v41
	v_fmac_f32_e32 v36, v38, v38
	v_mul_f32_e32 v33, v33, v33
	v_add_f32_e32 v44, v45, v44
	v_fmac_f32_e32 v41, v40, v40
	v_add_f32_e32 v36, v37, v36
	v_fmac_f32_e32 v33, v32, v32
	v_add_f32_e32 v40, v44, v41
	v_mul_f32_e32 v41, v43, v43
	v_add_f32_e32 v32, v36, v33
	v_mul_f32_e32 v33, v35, v35
	v_fmac_f32_e32 v41, v42, v42
	v_fmac_f32_e32 v33, v34, v34
	v_add_f32_e32 v40, v41, v40
	v_add_f32_e32 v32, v33, v32
	v_add_f32_e32 v32, v40, v32
	v_mov_b32_e32 v33, v32
	s_nop 1
	v_permlane16_swap_b32_e32 v33, v32
	s_waitcnt lgkmcnt(0)
	v_add_f32_e32 v32, v32, v33
	v_mov_b32_e32 v33, v32
	s_nop 1
	v_permlane32_swap_b32_e32 v33, v32
	s_and_saveexec_b64 s[50:51], s[42:43]
	s_cbranch_execz .LBB0_964
	v_lshlrev_b64 v[34:35], 7, v[130:131]
	v_lshl_add_u64 v[34:35], s[94:95], 0, v[34:35]
	v_lshl_add_u64 v[34:35], s[48:49], 2, v[34:35]
	s_lshl_b32 s30, s56, 2
	v_lshl_add_u64 v[34:35], v[34:35], 0, s[30:31]
	s_waitcnt lgkmcnt(0)
	v_add_f32_e32 v32, v32, v33
	global_store_dword v[34:35], v32, off

.LBB0_968:
	v_mul_f32_e32 v29, v29, v29
	v_mul_f32_e32 v21, v21, v21
	v_fmac_f32_e32 v29, v28, v28
	v_mul_f32_e32 v28, v31, v31
	v_fmac_f32_e32 v21, v20, v20
	v_mul_f32_e32 v20, v23, v23
	v_fmac_f32_e32 v28, v30, v30
	v_mul_f32_e32 v25, v25, v25
	v_fmac_f32_e32 v20, v22, v22
	v_mul_f32_e32 v17, v17, v17
	v_add_f32_e32 v28, v29, v28
	v_fmac_f32_e32 v25, v24, v24
	v_add_f32_e32 v20, v21, v20
	v_fmac_f32_e32 v17, v16, v16
	v_add_f32_e32 v24, v28, v25
	v_mul_f32_e32 v25, v27, v27
	v_add_f32_e32 v16, v20, v17
	v_mul_f32_e32 v17, v19, v19
	v_fmac_f32_e32 v25, v26, v26
	v_fmac_f32_e32 v17, v18, v18
	v_add_f32_e32 v24, v25, v24
	v_add_f32_e32 v16, v17, v16
	v_add_f32_e32 v16, v24, v16
	v_mov_b32_e32 v17, v16
	s_nop 1
	v_permlane16_swap_b32_e32 v17, v16
	s_waitcnt lgkmcnt(0)
	v_add_f32_e32 v16, v16, v17
	v_mov_b32_e32 v17, v16
	s_nop 1
	v_permlane32_swap_b32_e32 v17, v16
	s_and_saveexec_b64 s[50:51], s[42:43]
	s_cbranch_execz .LBB0_970
	v_lshlrev_b64 v[18:19], 7, v[126:127]
	v_lshl_add_u64 v[18:19], s[94:95], 0, v[18:19]
	v_lshl_add_u64 v[18:19], s[48:49], 2, v[18:19]
	s_lshl_b32 s30, s56, 2
	v_lshl_add_u64 v[18:19], v[18:19], 0, s[30:31]
	s_waitcnt lgkmcnt(0)
	v_add_f32_e32 v16, v16, v17
	global_store_dword v[18:19], v16, off

.LBB0_974:
	v_mul_f32_e32 v13, v13, v13
	v_mul_f32_e32 v5, v5, v5
	v_fmac_f32_e32 v13, v12, v12
	v_mul_f32_e32 v12, v15, v15
	v_fmac_f32_e32 v5, v4, v4
	v_mul_f32_e32 v4, v7, v7
	v_fmac_f32_e32 v12, v14, v14
	v_mul_f32_e32 v9, v9, v9
	v_fmac_f32_e32 v4, v6, v6
	v_mul_f32_e32 v1, v1, v1
	v_add_f32_e32 v12, v13, v12
	v_fmac_f32_e32 v9, v8, v8
	v_add_f32_e32 v4, v5, v4
	v_fmac_f32_e32 v1, v0, v0
	v_add_f32_e32 v8, v12, v9
	v_mul_f32_e32 v9, v11, v11
	v_add_f32_e32 v0, v4, v1
	v_mul_f32_e32 v1, v3, v3
	v_fmac_f32_e32 v9, v10, v10
	v_fmac_f32_e32 v1, v2, v2
	v_add_f32_e32 v8, v9, v8
	v_add_f32_e32 v0, v1, v0
	v_add_f32_e32 v0, v8, v0
	v_mov_b32_e32 v1, v0
	s_nop 1
	v_permlane16_swap_b32_e32 v1, v0
	s_waitcnt lgkmcnt(0)
	v_add_f32_e32 v0, v0, v1
	v_mov_b32_e32 v1, v0
	s_nop 1
	v_permlane32_swap_b32_e32 v1, v0
	s_and_saveexec_b64 s[40:41], s[42:43]
	s_cbranch_execz .LBB0_917
	v_lshlrev_b64 v[2:3], 7, v[124:125]
	v_lshl_add_u64 v[2:3], s[94:95], 0, v[2:3]
	v_lshl_add_u64 v[2:3], s[48:49], 2, v[2:3]
	s_lshl_b32 s30, s56, 2
	v_lshl_add_u64 v[2:3], v[2:3], 0, s[30:31]
	s_waitcnt lgkmcnt(0)
	v_add_f32_e32 v0, v0, v1
	global_store_dword v[2:3], v0, off
	s_branch .LBB0_917
